# k-loop sub-phases 0,1 peeled per tile with C=0 first MFMAs; accumulator clearing movs removed (all five gemm bodies)
# speedup vs baseline: 1.0110x; 1.0030x over previous
; #define PG8_STAGE(bufoff, gbase, voff) do { _Pragma("unroll") for (int _i = 0; _i < 2; ++_i) \
;         __builtin_amdgcn_global_load_lds((const unsigned*)((const char*)(gbase) + (voff)[_i]), (LAS unsigned*)(lds + (bufoff) + ldsw + _i * 8192), 16, 0, 0); } while (0)
; #define PG8_LDA(dst, b, h) do { _Pragma("unroll") for (int m = 0; m < 4; ++m) _Pragma("unroll") for (int k = 0; k < 2; ++k) dst[m][k] = *(const LAS bf16x8*)(lds + PG8_SA(b, h) + aoff + m * 2048 + k * 1024); } while (0)
; #define PG8_LDB(dst, b, h) do { _Pragma("unroll") for (int n = 0; n < 2; ++n) _Pragma("unroll") for (int k = 0; k < 2; ++k) dst[n][k] = *(const LAS bf16x8*)(lds + PG8_SB(b, h) + boff + n * 2048 + k * 1024); } while (0)
; #define PG8_MMA(ai, bj, At, Bt) do { __builtin_amdgcn_s_setprio(1); _Pragma("unroll") for (int m = 0; m < 4; ++m) _Pragma("unroll") for (int n = 0; n < 2; ++n) _Pragma("unroll") for (int k = 0; k < 2; ++k) \
;         acc[ai][bj][m][n] = __builtin_amdgcn_mfma_f32_16x16x32_bf16(Bt[n][k], At[m][k], acc[ai][bj][m][n], 0, 0, 0); __builtin_amdgcn_s_setprio(0); } while (0)
; #define PG8_WAIT_V(n) asm volatile("s_waitcnt vmcnt(" #n ")" ::: "memory")
; #define PG8_WAIT_L(n) asm volatile("s_waitcnt lgkmcnt(" #n ")" ::: "memory")
; #define PG8_BAR __builtin_amdgcn_s_barrier()
; #define PG8_SCHED __builtin_amdgcn_sched_barrier(0)
; template <class Epi>
; __device__ __forceinline__ void gemm_phase(LAS unsigned char* lds, const Gemm g, const StaticOrder& S, const Epi& E, const int tid) {
;     ...
;         const bool has_next = S.next(ui + 1, nxt);
;         const char* nA = has_next ? (const char*)g.A + (size_t)nxt.pm * tstepA + (size_t)((nxt.pn >> g.ashift) * g.astep) * 2 : cA; const char* nB = has_next ? (const char*)g.Bt + (size_t)nxt.pn * tstepB : cB;
;         for (int t = 0; t < nt; t += 2) {
;             const bool last = (t == nt - 2);
;             const char* a1 = cA + (size_t)(t + 1) * kstep;
;             const char* a2 = last ? nA : cA + (size_t)(t + 2) * kstep; const char* b2 = last ? nB : cB + (size_t)(t + 2) * kstep;
;             const char* a3 = a2 + kstep; const char* b3 = b2 + kstep;
;             PG8_LDB(B0, 0, 0); PG8_LDB(B1, 0, 1); PG8_SCHED; PG8_LDA(At, 0, 0); PG8_STAGE(PG8_SA(1, 1), a1 + hstepA, voffA);
;             PG8_WAIT_V(8); PG8_WAIT_L(0); PG8_BAR; PG8_MMA(0, 0, At, B0); PG8_MMA(0, 1, At, B1); PG8_BAR; PG8_SCHED;
.LBB0_183:
	v_mov_b32_e32 v137, 0
	s_andn2_b64 vcc, exec, s[96:97]
	s_cbranch_vccnz .LBB0_187
	s_add_u32 s0, s36, 0x100
	s_addc_u32 s1, s37, 0
	s_add_u32 s6, s38, 0x80
	s_addc_u32 s7, s39, 0
	s_mov_b32 s36, 0
	s_add_i32 s38, s36, 2
	s_add_u32 s39, s6, 0x80
	s_addc_u32 s37, s7, 0
	s_add_i32 s62, 0, 0x10000
	s_cmp_eq_u32 s53, s36
	s_cselect_b32 s37, s31, s37
	s_cselect_b32 s36, s30, s39
	s_cselect_b32 s61, s35, s1
	s_cselect_b32 s60, s34, s0
	s_add_i32 s39, 0, 0x14000
	v_add_u32_e32 v152, s62, v168
	v_add_u32_e32 v170, s39, v168
	ds_read_b128 v[82:85], v152
	ds_read_b128 v[86:89], v152 offset:1024
	ds_read_b128 v[138:141], v152 offset:2048
	ds_read_b128 v[152:155], v152 offset:3072
	ds_read_b128 v[156:159], v170
	ds_read_b128 v[160:163], v170 offset:1024
	ds_read_b128 v[164:167], v170 offset:2048
	ds_read_b128 v[170:173], v170 offset:3072
	v_lshl_add_u64 v[194:195], s[6:7], 0, v[150:151]
	s_add_i32 m0, s44, 0xc000
	ds_read_b128 v[174:177], v169
	ds_read_b128 v[178:181], v169 offset:1024
	ds_read_b128 v[182:185], v169 offset:2048
	ds_read_b128 v[186:189], v169 offset:3072
	ds_read_b128 v[190:193], v169 offset:4096
	ds_read_b128 v[202:205], v169 offset:5120
	ds_read_b128 v[206:209], v169 offset:6144
	ds_read_b128 v[210:213], v169 offset:7168
	global_load_lds_dwordx4 v[194:195], off
	v_lshl_add_u64 v[194:195], s[6:7], 0, v[148:149]
	s_add_i32 m0, s44, 0xe000
	s_nop 0
	global_load_lds_dwordx4 v[194:195], off
	s_waitcnt vmcnt(8)
	s_waitcnt lgkmcnt(0)
	s_barrier
	s_setprio 1
	s_waitcnt lgkmcnt(0)
	v_mfma_f32_16x16x32_bf16 v[134:137], v[82:85], v[174:177], 0
	v_mfma_f32_16x16x32_bf16 v[62:65], v[138:141], v[174:177], 0
	v_mfma_f32_16x16x32_bf16 v[126:129], v[82:85], v[182:185], 0
	v_mfma_f32_16x16x32_bf16 v[54:57], v[138:141], v[182:185], 0
	v_mfma_f32_16x16x32_bf16 v[118:121], v[82:85], v[190:193], 0
	v_mfma_f32_16x16x32_bf16 v[46:49], v[138:141], v[190:193], 0
	v_mfma_f32_16x16x32_bf16 v[110:113], v[82:85], v[206:209], 0
	v_mfma_f32_16x16x32_bf16 v[38:41], v[138:141], v[206:209], 0
	v_mfma_f32_16x16x32_bf16 v[134:137], v[86:89], v[178:181], v[134:137]
	v_mfma_f32_16x16x32_bf16 v[62:65], v[152:155], v[178:181], v[62:65]
	v_mfma_f32_16x16x32_bf16 v[126:129], v[86:89], v[186:189], v[126:129]
	v_mfma_f32_16x16x32_bf16 v[54:57], v[152:155], v[186:189], v[54:57]
	v_mfma_f32_16x16x32_bf16 v[118:121], v[86:89], v[202:205], v[118:121]
	v_mfma_f32_16x16x32_bf16 v[46:49], v[152:155], v[202:205], v[46:49]
	v_mfma_f32_16x16x32_bf16 v[110:113], v[86:89], v[210:213], v[110:113]
	v_mfma_f32_16x16x32_bf16 v[38:41], v[152:155], v[210:213], v[38:41]
	s_setprio 0
	s_setprio 1
	v_mfma_f32_16x16x32_bf16 v[130:133], v[156:159], v[174:177], 0
	v_mfma_f32_16x16x32_bf16 v[58:61], v[164:167], v[174:177], 0
	v_mfma_f32_16x16x32_bf16 v[122:125], v[156:159], v[182:185], 0
	v_mfma_f32_16x16x32_bf16 v[50:53], v[164:167], v[182:185], 0
	v_mfma_f32_16x16x32_bf16 v[114:117], v[156:159], v[190:193], 0
	v_mfma_f32_16x16x32_bf16 v[42:45], v[164:167], v[190:193], 0
	v_mfma_f32_16x16x32_bf16 v[106:109], v[156:159], v[206:209], 0
	v_mfma_f32_16x16x32_bf16 v[34:37], v[164:167], v[206:209], 0
	v_mfma_f32_16x16x32_bf16 v[130:133], v[160:163], v[178:181], v[130:133]
	v_mfma_f32_16x16x32_bf16 v[58:61], v[170:173], v[178:181], v[58:61]
	v_mfma_f32_16x16x32_bf16 v[122:125], v[160:163], v[186:189], v[122:125]
	v_mfma_f32_16x16x32_bf16 v[50:53], v[170:173], v[186:189], v[50:53]
	v_mfma_f32_16x16x32_bf16 v[114:117], v[160:163], v[202:205], v[114:117]
	v_mfma_f32_16x16x32_bf16 v[42:45], v[170:173], v[202:205], v[42:45]
	v_mfma_f32_16x16x32_bf16 v[106:109], v[160:163], v[210:213], v[106:109]
	v_mfma_f32_16x16x32_bf16 v[34:37], v[170:173], v[210:213], v[34:37]
	s_setprio 0
	s_barrier
; #define PG8_STAGE(bufoff, gbase, voff) do { _Pragma("unroll") for (int _i = 0; _i < 2; ++_i) \
;         __builtin_amdgcn_global_load_lds((const unsigned*)((const char*)(gbase) + (voff)[_i]), (LAS unsigned*)(lds + (bufoff) + ldsw + _i * 8192), 16, 0, 0); } while (0)
; #define PG8_LDA(dst, b, h) do { _Pragma("unroll") for (int m = 0; m < 4; ++m) _Pragma("unroll") for (int k = 0; k < 2; ++k) dst[m][k] = *(const LAS bf16x8*)(lds + PG8_SA(b, h) + aoff + m * 2048 + k * 1024); } while (0)
; #define PG8_MMA(ai, bj, At, Bt) do { __builtin_amdgcn_s_setprio(1); _Pragma("unroll") for (int m = 0; m < 4; ++m) _Pragma("unroll") for (int n = 0; n < 2; ++n) _Pragma("unroll") for (int k = 0; k < 2; ++k) \
;         acc[ai][bj][m][n] = __builtin_amdgcn_mfma_f32_16x16x32_bf16(Bt[n][k], At[m][k], acc[ai][bj][m][n], 0, 0, 0); __builtin_amdgcn_s_setprio(0); } while (0)
; #define PG8_WAIT_V(n) asm volatile("s_waitcnt vmcnt(" #n ")" ::: "memory")
; #define PG8_WAIT_L(n) asm volatile("s_waitcnt lgkmcnt(" #n ")" ::: "memory")
; #define PG8_BAR __builtin_amdgcn_s_barrier()
; #define PG8_SCHED __builtin_amdgcn_sched_barrier(0)
; template <class Epi>
; __device__ __forceinline__ void gemm_phase(LAS unsigned char* lds, const Gemm g, const StaticOrder& S, const Epi& E, const int tid) {
;     ...
;             PG8_LDA(At, 0, 1); PG8_STAGE(PG8_SB(0, 0), b2, voffB); PG8_STAGE(PG8_SB(0, 1), b2 + hstepB, voffB); PG8_STAGE(PG8_SA(0, 0), a2, voffA);
;             PG8_WAIT_V(8); PG8_WAIT_L(0); PG8_BAR; PG8_MMA(1, 0, At, B0); PG8_MMA(1, 1, At, B1); PG8_BAR; PG8_SCHED;
	s_add_i32 s62, s62, s3
	v_lshl_add_u64 v[194:195], s[60:61], 0, v[0:1]
	s_mov_b32 m0, s62
	ds_read_b128 v[174:177], v169 offset:16384
	ds_read_b128 v[178:181], v169 offset:17408
	ds_read_b128 v[182:185], v169 offset:18432
	ds_read_b128 v[186:189], v169 offset:19456
	ds_read_b128 v[190:193], v169 offset:20480
	ds_read_b128 v[202:205], v169 offset:21504
	ds_read_b128 v[206:209], v169 offset:22528
	ds_read_b128 v[210:213], v169 offset:23552
	global_load_lds_dwordx4 v[194:195], off
	s_add_i32 m0, s62, 0x2000
	v_lshl_add_u64 v[196:197], s[60:61], 0, v[146:147]
	s_add_u32 s60, s60, s12
	s_addc_u32 s61, s61, s13
	s_add_i32 s39, s39, s3
	global_load_lds_dwordx4 v[196:197], off
	v_lshl_add_u64 v[198:199], s[60:61], 0, v[0:1]
	s_mov_b32 m0, s39
	v_lshl_add_u64 v[214:215], s[60:61], 0, v[146:147]
	global_load_lds_dwordx4 v[198:199], off
	s_add_i32 m0, s39, 0x2000
	v_lshl_add_u64 v[216:217], s[36:37], 0, v[142:143]
	global_load_lds_dwordx4 v[214:215], off
	s_mov_b32 m0, s44
	v_lshl_add_u64 v[218:219], s[36:37], 0, v[144:145]
	global_load_lds_dwordx4 v[216:217], off
	s_mov_b32 m0, s45
	s_nop 0
	global_load_lds_dwordx4 v[218:219], off
	s_waitcnt vmcnt(8)
	s_waitcnt lgkmcnt(0)
	s_barrier
	s_setprio 1
	s_waitcnt lgkmcnt(0)
	v_mfma_f32_16x16x32_bf16 v[102:105], v[82:85], v[174:177], 0
	v_mfma_f32_16x16x32_bf16 v[30:33], v[138:141], v[174:177], 0
	v_mfma_f32_16x16x32_bf16 v[94:97], v[82:85], v[182:185], 0
	v_mfma_f32_16x16x32_bf16 v[22:25], v[138:141], v[182:185], 0
	v_mfma_f32_16x16x32_bf16 v[78:81], v[82:85], v[190:193], 0
	v_mfma_f32_16x16x32_bf16 v[14:17], v[138:141], v[190:193], 0
	v_mfma_f32_16x16x32_bf16 v[70:73], v[82:85], v[206:209], 0
	v_mfma_f32_16x16x32_bf16 v[6:9], v[138:141], v[206:209], 0
	v_mfma_f32_16x16x32_bf16 v[102:105], v[86:89], v[178:181], v[102:105]
	v_mfma_f32_16x16x32_bf16 v[30:33], v[152:155], v[178:181], v[30:33]
	v_mfma_f32_16x16x32_bf16 v[94:97], v[86:89], v[186:189], v[94:97]
	v_mfma_f32_16x16x32_bf16 v[22:25], v[152:155], v[186:189], v[22:25]
	v_mfma_f32_16x16x32_bf16 v[78:81], v[86:89], v[202:205], v[78:81]
	v_mfma_f32_16x16x32_bf16 v[14:17], v[152:155], v[202:205], v[14:17]
	v_mfma_f32_16x16x32_bf16 v[70:73], v[86:89], v[210:213], v[70:73]
	v_mfma_f32_16x16x32_bf16 v[6:9], v[152:155], v[210:213], v[6:9]
	s_setprio 0
	s_setprio 1
	v_mfma_f32_16x16x32_bf16 v[26:29], v[164:167], v[174:177], 0
	v_mfma_f32_16x16x32_bf16 v[18:21], v[164:167], v[182:185], 0
	v_mfma_f32_16x16x32_bf16 v[74:77], v[156:159], v[190:193], 0
	v_mfma_f32_16x16x32_bf16 v[10:13], v[164:167], v[190:193], 0
	v_mfma_f32_16x16x32_bf16 v[66:69], v[156:159], v[206:209], 0
	v_mfma_f32_16x16x32_bf16 v[2:5], v[164:167], v[206:209], 0
	v_mfma_f32_16x16x32_bf16 v[82:85], v[156:159], v[174:177], 0
	v_mfma_f32_16x16x32_bf16 v[26:29], v[170:173], v[178:181], v[26:29]
	v_mfma_f32_16x16x32_bf16 v[86:89], v[156:159], v[182:185], 0
	v_mfma_f32_16x16x32_bf16 v[18:21], v[170:173], v[186:189], v[18:21]
	v_mfma_f32_16x16x32_bf16 v[74:77], v[160:163], v[202:205], v[74:77]
	v_mfma_f32_16x16x32_bf16 v[10:13], v[170:173], v[202:205], v[10:13]
	v_mfma_f32_16x16x32_bf16 v[66:69], v[160:163], v[210:213], v[66:69]
	v_mfma_f32_16x16x32_bf16 v[2:5], v[170:173], v[210:213], v[2:5]
	v_mfma_f32_16x16x32_bf16 v[82:85], v[160:163], v[178:181], v[82:85]
	v_mfma_f32_16x16x32_bf16 v[86:89], v[160:163], v[186:189], v[86:89]
	s_setprio 0
	s_barrier
	s_branch .Lkl185_sp2

; #define PG8_STAGE(bufoff, gbase, voff) do { _Pragma("unroll") for (int _i = 0; _i < 2; ++_i) \
;         __builtin_amdgcn_global_load_lds((const unsigned*)((const char*)(gbase) + (voff)[_i]), (LAS unsigned*)(lds + (bufoff) + ldsw + _i * 8192), 16, 0, 0); } while (0)
; #define PG8_LDA(dst, b, h) do { _Pragma("unroll") for (int m = 0; m < 4; ++m) _Pragma("unroll") for (int k = 0; k < 2; ++k) dst[m][k] = *(const LAS bf16x8*)(lds + PG8_SA(b, h) + aoff + m * 2048 + k * 1024); } while (0)
; #define PG8_LDB(dst, b, h) do { _Pragma("unroll") for (int n = 0; n < 2; ++n) _Pragma("unroll") for (int k = 0; k < 2; ++k) dst[n][k] = *(const LAS bf16x8*)(lds + PG8_SB(b, h) + boff + n * 2048 + k * 1024); } while (0)
; #define PG8_MMA(ai, bj, At, Bt) do { __builtin_amdgcn_s_setprio(1); _Pragma("unroll") for (int m = 0; m < 4; ++m) _Pragma("unroll") for (int n = 0; n < 2; ++n) _Pragma("unroll") for (int k = 0; k < 2; ++k) \
;         acc[ai][bj][m][n] = __builtin_amdgcn_mfma_f32_16x16x32_bf16(Bt[n][k], At[m][k], acc[ai][bj][m][n], 0, 0, 0); __builtin_amdgcn_s_setprio(0); } while (0)
; #define PG8_WAIT_V(n) asm volatile("s_waitcnt vmcnt(" #n ")" ::: "memory")
; #define PG8_WAIT_L(n) asm volatile("s_waitcnt lgkmcnt(" #n ")" ::: "memory")
; #define PG8_BAR __builtin_amdgcn_s_barrier()
; #define PG8_SCHED __builtin_amdgcn_sched_barrier(0)
; template <class Epi>
; __device__ __forceinline__ void gemm_phase(LAS unsigned char* lds, const Gemm g, const StaticOrder& S, const Epi& E, const int tid) {
;     ...
;             PG8_LDB(B0, 1, 0); PG8_LDB(B1, 1, 1); PG8_SCHED; PG8_LDA(At, 1, 0); PG8_STAGE(PG8_SA(0, 1), a2 + hstepA, voffA);
;             PG8_WAIT_V(8); PG8_WAIT_L(0); PG8_BAR; PG8_MMA(0, 0, At, B0); PG8_MMA(0, 1, At, B1); PG8_BAR; PG8_SCHED;
.Lkl185_sp2:
	s_add_i32 s39, 0, 0x18000
	s_add_i32 s60, 0, 0x1c000
	v_add_u32_e32 v152, s39, v168
	v_add_u32_e32 v170, s60, v168
	ds_read_b128 v[90:93], v152
	ds_read_b128 v[98:101], v152 offset:1024
	ds_read_b128 v[138:141], v152 offset:2048
	ds_read_b128 v[152:155], v152 offset:3072
	ds_read_b128 v[156:159], v170
	ds_read_b128 v[160:163], v170 offset:1024
	ds_read_b128 v[164:167], v170 offset:2048
	ds_read_b128 v[170:173], v170 offset:3072
	s_add_u32 s36, s36, s10
	s_addc_u32 s37, s37, s11
	s_mov_b32 m0, s46
	v_lshl_add_u64 v[220:221], s[36:37], 0, v[142:143]
	ds_read_b128 v[174:177], v169 offset:32768
	ds_read_b128 v[178:181], v169 offset:33792
	ds_read_b128 v[182:185], v169 offset:34816
	ds_read_b128 v[186:189], v169 offset:35840
	ds_read_b128 v[190:193], v169 offset:36864
	ds_read_b128 v[202:205], v169 offset:37888
	ds_read_b128 v[206:209], v169 offset:38912
	ds_read_b128 v[210:213], v169 offset:39936
	global_load_lds_dwordx4 v[220:221], off
	v_lshl_add_u64 v[220:221], s[36:37], 0, v[144:145]
	s_mov_b32 m0, s47
	s_nop 0
	global_load_lds_dwordx4 v[220:221], off
	s_waitcnt vmcnt(8)
	s_waitcnt lgkmcnt(0)
	s_barrier
	s_setprio 1
	s_waitcnt lgkmcnt(0)
	v_mfma_f32_16x16x32_bf16 v[134:137], v[90:93], v[174:177], v[134:137]
	v_mfma_f32_16x16x32_bf16 v[62:65], v[138:141], v[174:177], v[62:65]
	v_mfma_f32_16x16x32_bf16 v[126:129], v[90:93], v[182:185], v[126:129]
	v_mfma_f32_16x16x32_bf16 v[54:57], v[138:141], v[182:185], v[54:57]
	v_mfma_f32_16x16x32_bf16 v[118:121], v[90:93], v[190:193], v[118:121]
	v_mfma_f32_16x16x32_bf16 v[46:49], v[138:141], v[190:193], v[46:49]
	v_mfma_f32_16x16x32_bf16 v[110:113], v[90:93], v[206:209], v[110:113]
	v_mfma_f32_16x16x32_bf16 v[38:41], v[138:141], v[206:209], v[38:41]
	v_mfma_f32_16x16x32_bf16 v[134:137], v[98:101], v[178:181], v[134:137]
	v_mfma_f32_16x16x32_bf16 v[62:65], v[152:155], v[178:181], v[62:65]
	v_mfma_f32_16x16x32_bf16 v[126:129], v[98:101], v[186:189], v[126:129]
	v_mfma_f32_16x16x32_bf16 v[54:57], v[152:155], v[186:189], v[54:57]
	v_mfma_f32_16x16x32_bf16 v[118:121], v[98:101], v[202:205], v[118:121]
	v_mfma_f32_16x16x32_bf16 v[46:49], v[152:155], v[202:205], v[46:49]
	v_mfma_f32_16x16x32_bf16 v[110:113], v[98:101], v[210:213], v[110:113]
	v_mfma_f32_16x16x32_bf16 v[38:41], v[152:155], v[210:213], v[38:41]
	s_setprio 0
	s_setprio 1
	v_mfma_f32_16x16x32_bf16 v[130:133], v[156:159], v[174:177], v[130:133]
	v_mfma_f32_16x16x32_bf16 v[58:61], v[164:167], v[174:177], v[58:61]
	v_mfma_f32_16x16x32_bf16 v[122:125], v[156:159], v[182:185], v[122:125]
	v_mfma_f32_16x16x32_bf16 v[50:53], v[164:167], v[182:185], v[50:53]
	v_mfma_f32_16x16x32_bf16 v[114:117], v[156:159], v[190:193], v[114:117]
	v_mfma_f32_16x16x32_bf16 v[42:45], v[164:167], v[190:193], v[42:45]
	v_mfma_f32_16x16x32_bf16 v[106:109], v[156:159], v[206:209], v[106:109]
	v_mfma_f32_16x16x32_bf16 v[34:37], v[164:167], v[206:209], v[34:37]
	v_mfma_f32_16x16x32_bf16 v[130:133], v[160:163], v[178:181], v[130:133]
	v_mfma_f32_16x16x32_bf16 v[58:61], v[170:173], v[178:181], v[58:61]
	v_mfma_f32_16x16x32_bf16 v[122:125], v[160:163], v[186:189], v[122:125]
	v_mfma_f32_16x16x32_bf16 v[50:53], v[170:173], v[186:189], v[50:53]
	v_mfma_f32_16x16x32_bf16 v[114:117], v[160:163], v[202:205], v[114:117]
	v_mfma_f32_16x16x32_bf16 v[42:45], v[170:173], v[202:205], v[42:45]
	v_mfma_f32_16x16x32_bf16 v[106:109], v[160:163], v[210:213], v[106:109]
	v_mfma_f32_16x16x32_bf16 v[34:37], v[170:173], v[210:213], v[34:37]
	s_setprio 0
	s_barrier
; #define PG8_STAGE(bufoff, gbase, voff) do { _Pragma("unroll") for (int _i = 0; _i < 2; ++_i) \
;         __builtin_amdgcn_global_load_lds((const unsigned*)((const char*)(gbase) + (voff)[_i]), (LAS unsigned*)(lds + (bufoff) + ldsw + _i * 8192), 16, 0, 0); } while (0)
; #define PG8_LDA(dst, b, h) do { _Pragma("unroll") for (int m = 0; m < 4; ++m) _Pragma("unroll") for (int k = 0; k < 2; ++k) dst[m][k] = *(const LAS bf16x8*)(lds + PG8_SA(b, h) + aoff + m * 2048 + k * 1024); } while (0)
; #define PG8_MMA(ai, bj, At, Bt) do { __builtin_amdgcn_s_setprio(1); _Pragma("unroll") for (int m = 0; m < 4; ++m) _Pragma("unroll") for (int n = 0; n < 2; ++n) _Pragma("unroll") for (int k = 0; k < 2; ++k) \
;         acc[ai][bj][m][n] = __builtin_amdgcn_mfma_f32_16x16x32_bf16(Bt[n][k], At[m][k], acc[ai][bj][m][n], 0, 0, 0); __builtin_amdgcn_s_setprio(0); } while (0)
; #define PG8_WAIT_V(n) asm volatile("s_waitcnt vmcnt(" #n ")" ::: "memory")
; #define PG8_WAIT_L(n) asm volatile("s_waitcnt lgkmcnt(" #n ")" ::: "memory")
; #define PG8_BAR __builtin_amdgcn_s_barrier()
; #define PG8_SCHED __builtin_amdgcn_sched_barrier(0)
; template <class Epi>
; __device__ __forceinline__ void gemm_phase(LAS unsigned char* lds, const Gemm g, const StaticOrder& S, const Epi& E, const int tid) {
;     ...
;             PG8_LDA(At, 1, 1); PG8_STAGE(PG8_SB(1, 0), b3, voffB); PG8_STAGE(PG8_SB(1, 1), b3 + hstepB, voffB); PG8_STAGE(PG8_SA(1, 0), a3, voffA);
;             PG8_WAIT_V(8); PG8_WAIT_L(0); PG8_BAR; PG8_MMA(1, 0, At, B0); PG8_MMA(1, 1, At, B1); PG8_BAR; PG8_SCHED;
;         }
	s_add_i32 s36, s39, s3
	v_lshl_add_u64 v[194:195], v[194:195], 0, s[80:81]
	s_mov_b32 m0, s36
	ds_read_b128 v[174:177], v169 offset:49152
	ds_read_b128 v[178:181], v169 offset:50176
	ds_read_b128 v[182:185], v169 offset:51200
	ds_read_b128 v[186:189], v169 offset:52224
	ds_read_b128 v[190:193], v169 offset:53248
	ds_read_b128 v[202:205], v169 offset:54272
	ds_read_b128 v[206:209], v169 offset:55296
	ds_read_b128 v[210:213], v169 offset:56320
	global_load_lds_dwordx4 v[194:195], off
	v_lshl_add_u64 v[194:195], v[196:197], 0, s[80:81]
	s_add_i32 m0, s36, 0x2000
	s_add_i32 s36, s60, s3
	global_load_lds_dwordx4 v[194:195], off
	v_lshl_add_u64 v[194:195], v[198:199], 0, s[80:81]
	s_mov_b32 m0, s36
	s_nop 0
	global_load_lds_dwordx4 v[194:195], off
	v_lshl_add_u64 v[194:195], v[214:215], 0, s[80:81]
	s_add_i32 m0, s36, 0x2000
	s_nop 0
	global_load_lds_dwordx4 v[194:195], off
	v_lshl_add_u64 v[194:195], v[216:217], 0, s[80:81]
	s_mov_b32 m0, s51
	s_nop 0
	global_load_lds_dwordx4 v[194:195], off
	v_lshl_add_u64 v[194:195], v[218:219], 0, s[80:81]
	s_mov_b32 m0, s52
	s_nop 0
	global_load_lds_dwordx4 v[194:195], off
	s_waitcnt vmcnt(8)
	s_waitcnt lgkmcnt(0)
	s_barrier
	s_setprio 1
	s_waitcnt lgkmcnt(0)
	v_mfma_f32_16x16x32_bf16 v[102:105], v[90:93], v[174:177], v[102:105]
	v_mfma_f32_16x16x32_bf16 v[30:33], v[138:141], v[174:177], v[30:33]
	v_mfma_f32_16x16x32_bf16 v[94:97], v[90:93], v[182:185], v[94:97]
	v_mfma_f32_16x16x32_bf16 v[22:25], v[138:141], v[182:185], v[22:25]
	v_mfma_f32_16x16x32_bf16 v[78:81], v[90:93], v[190:193], v[78:81]
	v_mfma_f32_16x16x32_bf16 v[14:17], v[138:141], v[190:193], v[14:17]
	v_mfma_f32_16x16x32_bf16 v[70:73], v[90:93], v[206:209], v[70:73]
	v_mfma_f32_16x16x32_bf16 v[6:9], v[138:141], v[206:209], v[6:9]
	v_mfma_f32_16x16x32_bf16 v[102:105], v[98:101], v[178:181], v[102:105]
	v_mfma_f32_16x16x32_bf16 v[30:33], v[152:155], v[178:181], v[30:33]
	v_mfma_f32_16x16x32_bf16 v[94:97], v[98:101], v[186:189], v[94:97]
	v_mfma_f32_16x16x32_bf16 v[22:25], v[152:155], v[186:189], v[22:25]
	v_mfma_f32_16x16x32_bf16 v[78:81], v[98:101], v[202:205], v[78:81]
	v_mfma_f32_16x16x32_bf16 v[14:17], v[152:155], v[202:205], v[14:17]
	v_mfma_f32_16x16x32_bf16 v[70:73], v[98:101], v[210:213], v[70:73]
	v_mfma_f32_16x16x32_bf16 v[6:9], v[152:155], v[210:213], v[6:9]
	s_setprio 0
	s_setprio 1
	v_mfma_f32_16x16x32_bf16 v[82:85], v[156:159], v[174:177], v[82:85]
	v_mfma_f32_16x16x32_bf16 v[98:101], v[160:163], v[178:181], v[82:85]
	v_mfma_f32_16x16x32_bf16 v[26:29], v[164:167], v[174:177], v[26:29]
	v_mfma_f32_16x16x32_bf16 v[82:85], v[156:159], v[182:185], v[86:89]
	v_mfma_f32_16x16x32_bf16 v[18:21], v[164:167], v[182:185], v[18:21]
	v_mfma_f32_16x16x32_bf16 v[74:77], v[156:159], v[190:193], v[74:77]
	v_mfma_f32_16x16x32_bf16 v[10:13], v[164:167], v[190:193], v[10:13]
	v_mfma_f32_16x16x32_bf16 v[66:69], v[156:159], v[206:209], v[66:69]
	v_mfma_f32_16x16x32_bf16 v[2:5], v[164:167], v[206:209], v[2:5]
	v_mfma_f32_16x16x32_bf16 v[26:29], v[170:173], v[178:181], v[26:29]
	v_mfma_f32_16x16x32_bf16 v[90:93], v[160:163], v[186:189], v[82:85]
	v_mfma_f32_16x16x32_bf16 v[18:21], v[170:173], v[186:189], v[18:21]
	v_mfma_f32_16x16x32_bf16 v[74:77], v[160:163], v[202:205], v[74:77]
	v_mfma_f32_16x16x32_bf16 v[10:13], v[170:173], v[202:205], v[10:13]
	v_mfma_f32_16x16x32_bf16 v[66:69], v[160:163], v[210:213], v[66:69]
	v_mfma_f32_16x16x32_bf16 v[2:5], v[170:173], v[210:213], v[2:5]
	s_setprio 0
	s_barrier
	s_add_u32 s0, s0, 0x100
	s_addc_u32 s1, s1, 0
	s_add_u32 s6, s6, 0x100
	s_addc_u32 s7, s7, 0
	s_cmp_ge_i32 s38, s48
	s_mov_b32 s36, s38
	s_cbranch_scc0 .LBB0_185
	s_movk_i32 s61, 0xf000
	s_mov_b32 s60, 0x800000

; #define PG8_STAGE(bufoff, gbase, voff) do { _Pragma("unroll") for (int _i = 0; _i < 2; ++_i) \
;         __builtin_amdgcn_global_load_lds((const unsigned*)((const char*)(gbase) + (voff)[_i]), (LAS unsigned*)(lds + (bufoff) + ldsw + _i * 8192), 16, 0, 0); } while (0)
; #define PG8_LDA(dst, b, h) do { _Pragma("unroll") for (int m = 0; m < 4; ++m) _Pragma("unroll") for (int k = 0; k < 2; ++k) dst[m][k] = *(const LAS bf16x8*)(lds + PG8_SA(b, h) + aoff + m * 2048 + k * 1024); } while (0)
; #define PG8_LDB(dst, b, h) do { _Pragma("unroll") for (int n = 0; n < 2; ++n) _Pragma("unroll") for (int k = 0; k < 2; ++k) dst[n][k] = *(const LAS bf16x8*)(lds + PG8_SB(b, h) + boff + n * 2048 + k * 1024); } while (0)
; #define PG8_MMA(ai, bj, At, Bt) do { __builtin_amdgcn_s_setprio(1); _Pragma("unroll") for (int m = 0; m < 4; ++m) _Pragma("unroll") for (int n = 0; n < 2; ++n) _Pragma("unroll") for (int k = 0; k < 2; ++k) \
;         acc[ai][bj][m][n] = __builtin_amdgcn_mfma_f32_16x16x32_bf16(Bt[n][k], At[m][k], acc[ai][bj][m][n], 0, 0, 0); __builtin_amdgcn_s_setprio(0); } while (0)
; #define PG8_WAIT_V(n) asm volatile("s_waitcnt vmcnt(" #n ")" ::: "memory")
; #define PG8_WAIT_L(n) asm volatile("s_waitcnt lgkmcnt(" #n ")" ::: "memory")
; #define PG8_BAR __builtin_amdgcn_s_barrier()
; #define PG8_SCHED __builtin_amdgcn_sched_barrier(0)
; template <class Epi>
; __device__ __forceinline__ void gemm_phase(LAS unsigned char* lds, const Gemm g, const StaticOrder& S, const Epi& E, const int tid) {
;     ...
;         const bool has_next = S.next(ui + 1, nxt);
;         const char* nA = has_next ? (const char*)g.A + (size_t)nxt.pm * tstepA + (size_t)((nxt.pn >> g.ashift) * g.astep) * 2 : cA; const char* nB = has_next ? (const char*)g.Bt + (size_t)nxt.pn * tstepB : cB;
;         for (int t = 0; t < nt; t += 2) {
;             const bool last = (t == nt - 2);
;             const char* a1 = cA + (size_t)(t + 1) * kstep;
;             const char* a2 = last ? nA : cA + (size_t)(t + 2) * kstep; const char* b2 = last ? nB : cB + (size_t)(t + 2) * kstep;
;             const char* a3 = a2 + kstep; const char* b3 = b2 + kstep;
;             PG8_LDB(B0, 0, 0); PG8_LDB(B1, 0, 1); PG8_SCHED; PG8_LDA(At, 0, 0); PG8_STAGE(PG8_SA(1, 1), a1 + hstepA, voffA);
;             PG8_WAIT_V(8); PG8_WAIT_L(0); PG8_BAR; PG8_MMA(0, 0, At, B0); PG8_MMA(0, 1, At, B1); PG8_BAR; PG8_SCHED;
.LBB0_296:
	v_mov_b32_e32 v125, 0
	s_andn2_b64 vcc, exec, s[24:25]
	s_cbranch_vccnz .LBB0_300
	s_add_u32 s0, s34, 0x100
	s_addc_u32 s1, s35, 0
	s_add_u32 s6, s36, 0x80
	s_addc_u32 s7, s37, 0
	s_mov_b32 s34, 0
	s_add_i32 s36, s34, 2
	s_add_u32 s37, s6, 0x80
	s_addc_u32 s35, s7, 0
	s_add_i32 s60, 0, 0x10000
	s_cmp_eq_u32 s51, s34
	s_cselect_b32 s35, s29, s35
	s_cselect_b32 s34, s28, s37
	s_cselect_b32 s59, s31, s1
	s_cselect_b32 s58, s30, s0
	s_add_i32 s37, 0, 0x14000
	v_add_u32_e32 v142, s60, v248
	v_add_u32_e32 v158, s37, v248
	ds_read_b128 v[130:133], v142
	ds_read_b128 v[134:137], v142 offset:1024
	ds_read_b128 v[138:141], v142 offset:2048
	ds_read_b128 v[142:145], v142 offset:3072
	ds_read_b128 v[146:149], v158
	ds_read_b128 v[150:153], v158 offset:1024
	ds_read_b128 v[154:157], v158 offset:2048
	ds_read_b128 v[158:161], v158 offset:3072
	v_lshl_add_u64 v[212:213], s[6:7], 0, v[210:211]
	s_add_i32 m0, s38, 0xc000
	ds_read_b128 v[162:165], v194
	ds_read_b128 v[166:169], v194 offset:1024
	ds_read_b128 v[170:173], v194 offset:2048
	ds_read_b128 v[174:177], v194 offset:3072
	ds_read_b128 v[178:181], v194 offset:4096
	ds_read_b128 v[182:185], v194 offset:5120
	ds_read_b128 v[186:189], v194 offset:6144
	ds_read_b128 v[190:193], v194 offset:7168
	global_load_lds_dwordx4 v[212:213], off
	v_lshl_add_u64 v[212:213], s[6:7], 0, v[208:209]
	s_add_i32 m0, s38, 0xe000
	s_nop 0
	global_load_lds_dwordx4 v[212:213], off
	s_waitcnt vmcnt(8)
	s_waitcnt lgkmcnt(0)
	s_barrier
	s_setprio 1
	s_waitcnt lgkmcnt(0)
	v_mfma_f32_16x16x32_bf16 v[122:125], v[130:133], v[162:165], 0
	v_mfma_f32_16x16x32_bf16 v[126:129], v[138:141], v[162:165], 0
	v_mfma_f32_16x16x32_bf16 v[110:113], v[130:133], v[170:173], 0
	v_mfma_f32_16x16x32_bf16 v[106:109], v[138:141], v[170:173], 0
	v_mfma_f32_16x16x32_bf16 v[94:97], v[130:133], v[178:181], 0
	v_mfma_f32_16x16x32_bf16 v[90:93], v[138:141], v[178:181], 0
	v_mfma_f32_16x16x32_bf16 v[78:81], v[130:133], v[186:189], 0
	v_mfma_f32_16x16x32_bf16 v[74:77], v[138:141], v[186:189], 0
	v_mfma_f32_16x16x32_bf16 v[122:125], v[134:137], v[166:169], v[122:125]
	v_mfma_f32_16x16x32_bf16 v[126:129], v[142:145], v[166:169], v[126:129]
	v_mfma_f32_16x16x32_bf16 v[110:113], v[134:137], v[174:177], v[110:113]
	v_mfma_f32_16x16x32_bf16 v[106:109], v[142:145], v[174:177], v[106:109]
	v_mfma_f32_16x16x32_bf16 v[94:97], v[134:137], v[182:185], v[94:97]
	v_mfma_f32_16x16x32_bf16 v[90:93], v[142:145], v[182:185], v[90:93]
	v_mfma_f32_16x16x32_bf16 v[78:81], v[134:137], v[190:193], v[78:81]
	v_mfma_f32_16x16x32_bf16 v[74:77], v[142:145], v[190:193], v[74:77]
	s_setprio 0
	s_setprio 1
	v_mfma_f32_16x16x32_bf16 v[118:121], v[146:149], v[162:165], 0
	v_mfma_f32_16x16x32_bf16 v[114:117], v[154:157], v[162:165], 0
	v_mfma_f32_16x16x32_bf16 v[102:105], v[146:149], v[170:173], 0
	v_mfma_f32_16x16x32_bf16 v[98:101], v[154:157], v[170:173], 0
	v_mfma_f32_16x16x32_bf16 v[86:89], v[146:149], v[178:181], 0
	v_mfma_f32_16x16x32_bf16 v[82:85], v[154:157], v[178:181], 0
	v_mfma_f32_16x16x32_bf16 v[70:73], v[146:149], v[186:189], 0
	v_mfma_f32_16x16x32_bf16 v[66:69], v[154:157], v[186:189], 0
	v_mfma_f32_16x16x32_bf16 v[118:121], v[150:153], v[166:169], v[118:121]
	v_mfma_f32_16x16x32_bf16 v[114:117], v[158:161], v[166:169], v[114:117]
	v_mfma_f32_16x16x32_bf16 v[102:105], v[150:153], v[174:177], v[102:105]
	v_mfma_f32_16x16x32_bf16 v[98:101], v[158:161], v[174:177], v[98:101]
	v_mfma_f32_16x16x32_bf16 v[86:89], v[150:153], v[182:185], v[86:89]
	v_mfma_f32_16x16x32_bf16 v[82:85], v[158:161], v[182:185], v[82:85]
	v_mfma_f32_16x16x32_bf16 v[70:73], v[150:153], v[190:193], v[70:73]
	v_mfma_f32_16x16x32_bf16 v[66:69], v[158:161], v[190:193], v[66:69]
	s_setprio 0
	s_barrier
; #define PG8_STAGE(bufoff, gbase, voff) do { _Pragma("unroll") for (int _i = 0; _i < 2; ++_i) \
;         __builtin_amdgcn_global_load_lds((const unsigned*)((const char*)(gbase) + (voff)[_i]), (LAS unsigned*)(lds + (bufoff) + ldsw + _i * 8192), 16, 0, 0); } while (0)
; #define PG8_LDA(dst, b, h) do { _Pragma("unroll") for (int m = 0; m < 4; ++m) _Pragma("unroll") for (int k = 0; k < 2; ++k) dst[m][k] = *(const LAS bf16x8*)(lds + PG8_SA(b, h) + aoff + m * 2048 + k * 1024); } while (0)
; #define PG8_MMA(ai, bj, At, Bt) do { __builtin_amdgcn_s_setprio(1); _Pragma("unroll") for (int m = 0; m < 4; ++m) _Pragma("unroll") for (int n = 0; n < 2; ++n) _Pragma("unroll") for (int k = 0; k < 2; ++k) \
;         acc[ai][bj][m][n] = __builtin_amdgcn_mfma_f32_16x16x32_bf16(Bt[n][k], At[m][k], acc[ai][bj][m][n], 0, 0, 0); __builtin_amdgcn_s_setprio(0); } while (0)
; #define PG8_WAIT_V(n) asm volatile("s_waitcnt vmcnt(" #n ")" ::: "memory")
; #define PG8_WAIT_L(n) asm volatile("s_waitcnt lgkmcnt(" #n ")" ::: "memory")
; #define PG8_BAR __builtin_amdgcn_s_barrier()
; #define PG8_SCHED __builtin_amdgcn_sched_barrier(0)
; template <class Epi>
; __device__ __forceinline__ void gemm_phase(LAS unsigned char* lds, const Gemm g, const StaticOrder& S, const Epi& E, const int tid) {
;     ...
;             PG8_LDA(At, 0, 1); PG8_STAGE(PG8_SB(0, 0), b2, voffB); PG8_STAGE(PG8_SB(0, 1), b2 + hstepB, voffB); PG8_STAGE(PG8_SA(0, 0), a2, voffA);
;             PG8_WAIT_V(8); PG8_WAIT_L(0); PG8_BAR; PG8_MMA(1, 0, At, B0); PG8_MMA(1, 1, At, B1); PG8_BAR; PG8_SCHED;
	s_add_i32 s60, s60, s11
	v_lshl_add_u64 v[212:213], s[58:59], 0, v[0:1]
	s_mov_b32 m0, s60
	ds_read_b128 v[162:165], v194 offset:16384
	ds_read_b128 v[166:169], v194 offset:17408
	ds_read_b128 v[170:173], v194 offset:18432
	ds_read_b128 v[174:177], v194 offset:19456
	ds_read_b128 v[178:181], v194 offset:20480
	ds_read_b128 v[182:185], v194 offset:21504
	ds_read_b128 v[186:189], v194 offset:22528
	ds_read_b128 v[190:193], v194 offset:23552
	global_load_lds_dwordx4 v[212:213], off
	s_add_i32 m0, s60, 0x2000
	v_lshl_add_u64 v[214:215], s[58:59], 0, v[206:207]
	s_add_u32 s58, s58, s14
	s_addc_u32 s59, s59, s15
	s_add_i32 s37, s37, s11
	global_load_lds_dwordx4 v[214:215], off
	v_lshl_add_u64 v[216:217], s[58:59], 0, v[0:1]
	s_mov_b32 m0, s37
	v_lshl_add_u64 v[218:219], s[58:59], 0, v[206:207]
	global_load_lds_dwordx4 v[216:217], off
	s_add_i32 m0, s37, 0x2000
	v_lshl_add_u64 v[220:221], s[34:35], 0, v[202:203]
	global_load_lds_dwordx4 v[218:219], off
	s_mov_b32 m0, s38
	v_lshl_add_u64 v[222:223], s[34:35], 0, v[204:205]
	global_load_lds_dwordx4 v[220:221], off
	s_mov_b32 m0, s39
	s_nop 0
	global_load_lds_dwordx4 v[222:223], off
	s_waitcnt vmcnt(8)
	s_waitcnt lgkmcnt(0)
	s_barrier
	s_setprio 1
	s_waitcnt lgkmcnt(0)
	v_mfma_f32_16x16x32_bf16 v[62:65], v[130:133], v[162:165], 0
	v_mfma_f32_16x16x32_bf16 v[58:61], v[138:141], v[162:165], 0
	v_mfma_f32_16x16x32_bf16 v[46:49], v[130:133], v[170:173], 0
	v_mfma_f32_16x16x32_bf16 v[42:45], v[138:141], v[170:173], 0
	v_mfma_f32_16x16x32_bf16 v[30:33], v[130:133], v[178:181], 0
	v_mfma_f32_16x16x32_bf16 v[26:29], v[138:141], v[178:181], 0
	v_mfma_f32_16x16x32_bf16 v[14:17], v[130:133], v[186:189], 0
	v_mfma_f32_16x16x32_bf16 v[10:13], v[138:141], v[186:189], 0
	v_mfma_f32_16x16x32_bf16 v[62:65], v[134:137], v[166:169], v[62:65]
	v_mfma_f32_16x16x32_bf16 v[58:61], v[142:145], v[166:169], v[58:61]
	v_mfma_f32_16x16x32_bf16 v[46:49], v[134:137], v[174:177], v[46:49]
	v_mfma_f32_16x16x32_bf16 v[42:45], v[142:145], v[174:177], v[42:45]
	v_mfma_f32_16x16x32_bf16 v[30:33], v[134:137], v[182:185], v[30:33]
	v_mfma_f32_16x16x32_bf16 v[26:29], v[142:145], v[182:185], v[26:29]
	v_mfma_f32_16x16x32_bf16 v[14:17], v[134:137], v[190:193], v[14:17]
	v_mfma_f32_16x16x32_bf16 v[10:13], v[142:145], v[190:193], v[10:13]
	s_setprio 0
	s_setprio 1
	v_mfma_f32_16x16x32_bf16 v[54:57], v[146:149], v[162:165], 0
	v_mfma_f32_16x16x32_bf16 v[50:53], v[154:157], v[162:165], 0
	v_mfma_f32_16x16x32_bf16 v[38:41], v[146:149], v[170:173], 0
	v_mfma_f32_16x16x32_bf16 v[34:37], v[154:157], v[170:173], 0
	v_mfma_f32_16x16x32_bf16 v[22:25], v[146:149], v[178:181], 0
	v_mfma_f32_16x16x32_bf16 v[18:21], v[154:157], v[178:181], 0
	v_mfma_f32_16x16x32_bf16 v[6:9], v[146:149], v[186:189], 0
	v_mfma_f32_16x16x32_bf16 v[2:5], v[154:157], v[186:189], 0
	v_mfma_f32_16x16x32_bf16 v[54:57], v[150:153], v[166:169], v[54:57]
	v_mfma_f32_16x16x32_bf16 v[50:53], v[158:161], v[166:169], v[50:53]
	v_mfma_f32_16x16x32_bf16 v[38:41], v[150:153], v[174:177], v[38:41]
	v_mfma_f32_16x16x32_bf16 v[34:37], v[158:161], v[174:177], v[34:37]
	v_mfma_f32_16x16x32_bf16 v[22:25], v[150:153], v[182:185], v[22:25]
	v_mfma_f32_16x16x32_bf16 v[18:21], v[158:161], v[182:185], v[18:21]
	v_mfma_f32_16x16x32_bf16 v[6:9], v[150:153], v[190:193], v[6:9]
	v_mfma_f32_16x16x32_bf16 v[2:5], v[158:161], v[190:193], v[2:5]
	s_setprio 0
	s_barrier
	s_branch .Lkl298_sp2

; #define PG8_STAGE(bufoff, gbase, voff) do { _Pragma("unroll") for (int _i = 0; _i < 2; ++_i) \
;         __builtin_amdgcn_global_load_lds((const unsigned*)((const char*)(gbase) + (voff)[_i]), (LAS unsigned*)(lds + (bufoff) + ldsw + _i * 8192), 16, 0, 0); } while (0)
; #define PG8_LDA(dst, b, h) do { _Pragma("unroll") for (int m = 0; m < 4; ++m) _Pragma("unroll") for (int k = 0; k < 2; ++k) dst[m][k] = *(const LAS bf16x8*)(lds + PG8_SA(b, h) + aoff + m * 2048 + k * 1024); } while (0)
; #define PG8_LDB(dst, b, h) do { _Pragma("unroll") for (int n = 0; n < 2; ++n) _Pragma("unroll") for (int k = 0; k < 2; ++k) dst[n][k] = *(const LAS bf16x8*)(lds + PG8_SB(b, h) + boff + n * 2048 + k * 1024); } while (0)
; #define PG8_MMA(ai, bj, At, Bt) do { __builtin_amdgcn_s_setprio(1); _Pragma("unroll") for (int m = 0; m < 4; ++m) _Pragma("unroll") for (int n = 0; n < 2; ++n) _Pragma("unroll") for (int k = 0; k < 2; ++k) \
;         acc[ai][bj][m][n] = __builtin_amdgcn_mfma_f32_16x16x32_bf16(Bt[n][k], At[m][k], acc[ai][bj][m][n], 0, 0, 0); __builtin_amdgcn_s_setprio(0); } while (0)
; #define PG8_WAIT_V(n) asm volatile("s_waitcnt vmcnt(" #n ")" ::: "memory")
; #define PG8_WAIT_L(n) asm volatile("s_waitcnt lgkmcnt(" #n ")" ::: "memory")
; #define PG8_BAR __builtin_amdgcn_s_barrier()
; #define PG8_SCHED __builtin_amdgcn_sched_barrier(0)
; template <class Epi>
; __device__ __forceinline__ void gemm_phase(LAS unsigned char* lds, const Gemm g, const StaticOrder& S, const Epi& E, const int tid) {
;     ...
;             PG8_LDB(B0, 1, 0); PG8_LDB(B1, 1, 1); PG8_SCHED; PG8_LDA(At, 1, 0); PG8_STAGE(PG8_SA(0, 1), a2 + hstepA, voffA);
;             PG8_WAIT_V(8); PG8_WAIT_L(0); PG8_BAR; PG8_MMA(0, 0, At, B0); PG8_MMA(0, 1, At, B1); PG8_BAR; PG8_SCHED;
.Lkl298_sp2:
	s_add_i32 s37, 0, 0x18000
	s_add_i32 s58, 0, 0x1c000
	v_add_u32_e32 v142, s37, v248
	v_add_u32_e32 v158, s58, v248
	ds_read_b128 v[130:133], v142
	ds_read_b128 v[134:137], v142 offset:1024
	ds_read_b128 v[138:141], v142 offset:2048
	ds_read_b128 v[142:145], v142 offset:3072
	ds_read_b128 v[146:149], v158
	ds_read_b128 v[150:153], v158 offset:1024
	ds_read_b128 v[154:157], v158 offset:2048
	ds_read_b128 v[158:161], v158 offset:3072
	s_add_u32 s34, s34, s12
	s_addc_u32 s35, s35, s13
	s_mov_b32 m0, s43
	v_lshl_add_u64 v[224:225], s[34:35], 0, v[202:203]
	ds_read_b128 v[162:165], v194 offset:32768
	ds_read_b128 v[166:169], v194 offset:33792
	ds_read_b128 v[170:173], v194 offset:34816
	ds_read_b128 v[174:177], v194 offset:35840
	ds_read_b128 v[178:181], v194 offset:36864
	ds_read_b128 v[182:185], v194 offset:37888
	ds_read_b128 v[186:189], v194 offset:38912
	ds_read_b128 v[190:193], v194 offset:39936
	global_load_lds_dwordx4 v[224:225], off
	v_lshl_add_u64 v[224:225], s[34:35], 0, v[204:205]
	s_mov_b32 m0, s44
	s_nop 0
	global_load_lds_dwordx4 v[224:225], off
	s_waitcnt vmcnt(8)
	s_waitcnt lgkmcnt(0)
	s_barrier
	s_setprio 1
	s_waitcnt lgkmcnt(0)
	v_mfma_f32_16x16x32_bf16 v[122:125], v[130:133], v[162:165], v[122:125]
	v_mfma_f32_16x16x32_bf16 v[126:129], v[138:141], v[162:165], v[126:129]
	v_mfma_f32_16x16x32_bf16 v[110:113], v[130:133], v[170:173], v[110:113]
	v_mfma_f32_16x16x32_bf16 v[106:109], v[138:141], v[170:173], v[106:109]
	v_mfma_f32_16x16x32_bf16 v[94:97], v[130:133], v[178:181], v[94:97]
	v_mfma_f32_16x16x32_bf16 v[90:93], v[138:141], v[178:181], v[90:93]
	v_mfma_f32_16x16x32_bf16 v[78:81], v[130:133], v[186:189], v[78:81]
	v_mfma_f32_16x16x32_bf16 v[74:77], v[138:141], v[186:189], v[74:77]
	v_mfma_f32_16x16x32_bf16 v[122:125], v[134:137], v[166:169], v[122:125]
	v_mfma_f32_16x16x32_bf16 v[126:129], v[142:145], v[166:169], v[126:129]
	v_mfma_f32_16x16x32_bf16 v[110:113], v[134:137], v[174:177], v[110:113]
	v_mfma_f32_16x16x32_bf16 v[106:109], v[142:145], v[174:177], v[106:109]
	v_mfma_f32_16x16x32_bf16 v[94:97], v[134:137], v[182:185], v[94:97]
	v_mfma_f32_16x16x32_bf16 v[90:93], v[142:145], v[182:185], v[90:93]
	v_mfma_f32_16x16x32_bf16 v[78:81], v[134:137], v[190:193], v[78:81]
	v_mfma_f32_16x16x32_bf16 v[74:77], v[142:145], v[190:193], v[74:77]
	s_setprio 0
	s_setprio 1
	v_mfma_f32_16x16x32_bf16 v[118:121], v[146:149], v[162:165], v[118:121]
	v_mfma_f32_16x16x32_bf16 v[114:117], v[154:157], v[162:165], v[114:117]
	v_mfma_f32_16x16x32_bf16 v[102:105], v[146:149], v[170:173], v[102:105]
	v_mfma_f32_16x16x32_bf16 v[98:101], v[154:157], v[170:173], v[98:101]
	v_mfma_f32_16x16x32_bf16 v[86:89], v[146:149], v[178:181], v[86:89]
	v_mfma_f32_16x16x32_bf16 v[82:85], v[154:157], v[178:181], v[82:85]
	v_mfma_f32_16x16x32_bf16 v[70:73], v[146:149], v[186:189], v[70:73]
	v_mfma_f32_16x16x32_bf16 v[66:69], v[154:157], v[186:189], v[66:69]
	v_mfma_f32_16x16x32_bf16 v[118:121], v[150:153], v[166:169], v[118:121]
	v_mfma_f32_16x16x32_bf16 v[114:117], v[158:161], v[166:169], v[114:117]
	v_mfma_f32_16x16x32_bf16 v[102:105], v[150:153], v[174:177], v[102:105]
	v_mfma_f32_16x16x32_bf16 v[98:101], v[158:161], v[174:177], v[98:101]
	v_mfma_f32_16x16x32_bf16 v[86:89], v[150:153], v[182:185], v[86:89]
	v_mfma_f32_16x16x32_bf16 v[82:85], v[158:161], v[182:185], v[82:85]
	v_mfma_f32_16x16x32_bf16 v[70:73], v[150:153], v[190:193], v[70:73]
	v_mfma_f32_16x16x32_bf16 v[66:69], v[158:161], v[190:193], v[66:69]
	s_setprio 0
	s_barrier
; #define PG8_STAGE(bufoff, gbase, voff) do { _Pragma("unroll") for (int _i = 0; _i < 2; ++_i) \
;         __builtin_amdgcn_global_load_lds((const unsigned*)((const char*)(gbase) + (voff)[_i]), (LAS unsigned*)(lds + (bufoff) + ldsw + _i * 8192), 16, 0, 0); } while (0)
; #define PG8_LDA(dst, b, h) do { _Pragma("unroll") for (int m = 0; m < 4; ++m) _Pragma("unroll") for (int k = 0; k < 2; ++k) dst[m][k] = *(const LAS bf16x8*)(lds + PG8_SA(b, h) + aoff + m * 2048 + k * 1024); } while (0)
; #define PG8_MMA(ai, bj, At, Bt) do { __builtin_amdgcn_s_setprio(1); _Pragma("unroll") for (int m = 0; m < 4; ++m) _Pragma("unroll") for (int n = 0; n < 2; ++n) _Pragma("unroll") for (int k = 0; k < 2; ++k) \
;         acc[ai][bj][m][n] = __builtin_amdgcn_mfma_f32_16x16x32_bf16(Bt[n][k], At[m][k], acc[ai][bj][m][n], 0, 0, 0); __builtin_amdgcn_s_setprio(0); } while (0)
; #define PG8_WAIT_V(n) asm volatile("s_waitcnt vmcnt(" #n ")" ::: "memory")
; #define PG8_WAIT_L(n) asm volatile("s_waitcnt lgkmcnt(" #n ")" ::: "memory")
; #define PG8_BAR __builtin_amdgcn_s_barrier()
; #define PG8_SCHED __builtin_amdgcn_sched_barrier(0)
; template <class Epi>
; __device__ __forceinline__ void gemm_phase(LAS unsigned char* lds, const Gemm g, const StaticOrder& S, const Epi& E, const int tid) {
;     ...
;             PG8_LDA(At, 1, 1); PG8_STAGE(PG8_SB(1, 0), b3, voffB); PG8_STAGE(PG8_SB(1, 1), b3 + hstepB, voffB); PG8_STAGE(PG8_SA(1, 0), a3, voffA);
;             PG8_WAIT_V(8); PG8_WAIT_L(0); PG8_BAR; PG8_MMA(1, 0, At, B0); PG8_MMA(1, 1, At, B1); PG8_BAR; PG8_SCHED;
;         }
	s_add_i32 s34, s37, s11
	v_lshl_add_u64 v[212:213], v[212:213], 0, s[80:81]
	s_mov_b32 m0, s34
	ds_read_b128 v[162:165], v194 offset:49152
	ds_read_b128 v[166:169], v194 offset:50176
	ds_read_b128 v[170:173], v194 offset:51200
	ds_read_b128 v[174:177], v194 offset:52224
	ds_read_b128 v[178:181], v194 offset:53248
	ds_read_b128 v[182:185], v194 offset:54272
	ds_read_b128 v[186:189], v194 offset:55296
	ds_read_b128 v[190:193], v194 offset:56320
	global_load_lds_dwordx4 v[212:213], off
	v_lshl_add_u64 v[212:213], v[214:215], 0, s[80:81]
	s_add_i32 m0, s34, 0x2000
	s_add_i32 s34, s58, s11
	global_load_lds_dwordx4 v[212:213], off
	v_lshl_add_u64 v[212:213], v[216:217], 0, s[80:81]
	s_mov_b32 m0, s34
	s_nop 0
	global_load_lds_dwordx4 v[212:213], off
	v_lshl_add_u64 v[212:213], v[218:219], 0, s[80:81]
	s_add_i32 m0, s34, 0x2000
	s_nop 0
	global_load_lds_dwordx4 v[212:213], off
	v_lshl_add_u64 v[212:213], v[220:221], 0, s[80:81]
	s_mov_b32 m0, s49
	s_nop 0
	global_load_lds_dwordx4 v[212:213], off
	v_lshl_add_u64 v[212:213], v[222:223], 0, s[80:81]
	s_mov_b32 m0, s50
	s_nop 0
	global_load_lds_dwordx4 v[212:213], off
	s_waitcnt vmcnt(8)
	s_waitcnt lgkmcnt(0)
	s_barrier
	s_setprio 1
	s_waitcnt lgkmcnt(0)
	v_mfma_f32_16x16x32_bf16 v[62:65], v[130:133], v[162:165], v[62:65]
	v_mfma_f32_16x16x32_bf16 v[58:61], v[138:141], v[162:165], v[58:61]
	v_mfma_f32_16x16x32_bf16 v[46:49], v[130:133], v[170:173], v[46:49]
	v_mfma_f32_16x16x32_bf16 v[42:45], v[138:141], v[170:173], v[42:45]
	v_mfma_f32_16x16x32_bf16 v[30:33], v[130:133], v[178:181], v[30:33]
	v_mfma_f32_16x16x32_bf16 v[26:29], v[138:141], v[178:181], v[26:29]
	v_mfma_f32_16x16x32_bf16 v[14:17], v[130:133], v[186:189], v[14:17]
	v_mfma_f32_16x16x32_bf16 v[10:13], v[138:141], v[186:189], v[10:13]
	v_mfma_f32_16x16x32_bf16 v[62:65], v[134:137], v[166:169], v[62:65]
	v_mfma_f32_16x16x32_bf16 v[58:61], v[142:145], v[166:169], v[58:61]
	v_mfma_f32_16x16x32_bf16 v[46:49], v[134:137], v[174:177], v[46:49]
	v_mfma_f32_16x16x32_bf16 v[42:45], v[142:145], v[174:177], v[42:45]
	v_mfma_f32_16x16x32_bf16 v[30:33], v[134:137], v[182:185], v[30:33]
	v_mfma_f32_16x16x32_bf16 v[26:29], v[142:145], v[182:185], v[26:29]
	v_mfma_f32_16x16x32_bf16 v[14:17], v[134:137], v[190:193], v[14:17]
	v_mfma_f32_16x16x32_bf16 v[10:13], v[142:145], v[190:193], v[10:13]
	s_setprio 0
	s_setprio 1
	v_mfma_f32_16x16x32_bf16 v[54:57], v[146:149], v[162:165], v[54:57]
	v_mfma_f32_16x16x32_bf16 v[50:53], v[154:157], v[162:165], v[50:53]
	v_mfma_f32_16x16x32_bf16 v[38:41], v[146:149], v[170:173], v[38:41]
	v_mfma_f32_16x16x32_bf16 v[34:37], v[154:157], v[170:173], v[34:37]
	v_mfma_f32_16x16x32_bf16 v[22:25], v[146:149], v[178:181], v[22:25]
	v_mfma_f32_16x16x32_bf16 v[18:21], v[154:157], v[178:181], v[18:21]
	v_mfma_f32_16x16x32_bf16 v[6:9], v[146:149], v[186:189], v[6:9]
	v_mfma_f32_16x16x32_bf16 v[2:5], v[154:157], v[186:189], v[2:5]
	v_mfma_f32_16x16x32_bf16 v[54:57], v[150:153], v[166:169], v[54:57]
	v_mfma_f32_16x16x32_bf16 v[50:53], v[158:161], v[166:169], v[50:53]
	v_mfma_f32_16x16x32_bf16 v[38:41], v[150:153], v[174:177], v[38:41]
	v_mfma_f32_16x16x32_bf16 v[34:37], v[158:161], v[174:177], v[34:37]
	v_mfma_f32_16x16x32_bf16 v[22:25], v[150:153], v[182:185], v[22:25]
	v_mfma_f32_16x16x32_bf16 v[18:21], v[158:161], v[182:185], v[18:21]
	v_mfma_f32_16x16x32_bf16 v[6:9], v[150:153], v[190:193], v[6:9]
	v_mfma_f32_16x16x32_bf16 v[2:5], v[158:161], v[190:193], v[2:5]
	s_setprio 0
	s_barrier
	s_add_u32 s0, s0, 0x100
	s_addc_u32 s1, s1, 0
	s_add_u32 s6, s6, 0x100
	s_addc_u32 s7, s7, 0
	s_cmp_ge_i32 s36, s46
	s_mov_b32 s34, s36
	s_cbranch_scc0 .LBB0_298
	v_readlane_b32 s58, v254, 26
	v_readlane_b32 s59, v254, 27
	s_mov_b32 s60, 0x800000

; #define PG8_STAGE(bufoff, gbase, voff) do { _Pragma("unroll") for (int _i = 0; _i < 2; ++_i) \
;         __builtin_amdgcn_global_load_lds((const unsigned*)((const char*)(gbase) + (voff)[_i]), (LAS unsigned*)(lds + (bufoff) + ldsw + _i * 8192), 16, 0, 0); } while (0)
; #define PG8_LDA(dst, b, h) do { _Pragma("unroll") for (int m = 0; m < 4; ++m) _Pragma("unroll") for (int k = 0; k < 2; ++k) dst[m][k] = *(const LAS bf16x8*)(lds + PG8_SA(b, h) + aoff + m * 2048 + k * 1024); } while (0)
; #define PG8_LDB(dst, b, h) do { _Pragma("unroll") for (int n = 0; n < 2; ++n) _Pragma("unroll") for (int k = 0; k < 2; ++k) dst[n][k] = *(const LAS bf16x8*)(lds + PG8_SB(b, h) + boff + n * 2048 + k * 1024); } while (0)
; #define PG8_MMA(ai, bj, At, Bt) do { __builtin_amdgcn_s_setprio(1); _Pragma("unroll") for (int m = 0; m < 4; ++m) _Pragma("unroll") for (int n = 0; n < 2; ++n) _Pragma("unroll") for (int k = 0; k < 2; ++k) \
;         acc[ai][bj][m][n] = __builtin_amdgcn_mfma_f32_16x16x32_bf16(Bt[n][k], At[m][k], acc[ai][bj][m][n], 0, 0, 0); __builtin_amdgcn_s_setprio(0); } while (0)
; #define PG8_WAIT_V(n) asm volatile("s_waitcnt vmcnt(" #n ")" ::: "memory")
; #define PG8_WAIT_L(n) asm volatile("s_waitcnt lgkmcnt(" #n ")" ::: "memory")
; #define PG8_BAR __builtin_amdgcn_s_barrier()
; #define PG8_SCHED __builtin_amdgcn_sched_barrier(0)
; template <class Epi>
; __device__ __forceinline__ void gemm_phase(LAS unsigned char* lds, const Gemm g, const StaticOrder& S, const Epi& E, const int tid) {
;     ...
;         const bool has_next = S.next(ui + 1, nxt);
;         const char* nA = has_next ? (const char*)g.A + (size_t)nxt.pm * tstepA + (size_t)((nxt.pn >> g.ashift) * g.astep) * 2 : cA; const char* nB = has_next ? (const char*)g.Bt + (size_t)nxt.pn * tstepB : cB;
;         for (int t = 0; t < nt; t += 2) {
;             const bool last = (t == nt - 2);
;             const char* a1 = cA + (size_t)(t + 1) * kstep;
;             const char* a2 = last ? nA : cA + (size_t)(t + 2) * kstep; const char* b2 = last ? nB : cB + (size_t)(t + 2) * kstep;
;             const char* a3 = a2 + kstep; const char* b3 = b2 + kstep;
;             PG8_LDB(B0, 0, 0); PG8_LDB(B1, 0, 1); PG8_SCHED; PG8_LDA(At, 0, 0); PG8_STAGE(PG8_SA(1, 1), a1 + hstepA, voffA);
;             PG8_WAIT_V(8); PG8_WAIT_L(0); PG8_BAR; PG8_MMA(0, 0, At, B0); PG8_MMA(0, 1, At, B1); PG8_BAR; PG8_SCHED;
.LBB0_346:
	v_mov_b32_e32 v125, 0
	s_andn2_b64 vcc, exec, s[10:11]
	s_cbranch_vccnz .LBB0_349
	s_add_u32 s0, s36, 0x100
	s_addc_u32 s1, s37, 0
	s_add_u32 s36, s38, 0x80
	s_addc_u32 s37, s39, 0
	s_mov_b32 s38, 0
	s_add_i32 s62, s38, 2
	s_add_u32 s63, s36, 0x80
	s_addc_u32 s39, s37, 0
	s_add_i32 s66, 0, 0x10000
	s_cmp_eq_u32 s56, s38
	s_cselect_b32 s39, s7, s39
	s_cselect_b32 s38, s6, s63
	s_cselect_b32 s65, s31, s1
	s_cselect_b32 s64, s30, s0
	s_add_i32 s63, 0, 0x14000
	v_add_u32_e32 v142, s66, v234
	v_add_u32_e32 v158, s63, v234
	ds_read_b128 v[130:133], v142
	ds_read_b128 v[134:137], v142 offset:1024
	ds_read_b128 v[138:141], v142 offset:2048
	ds_read_b128 v[142:145], v142 offset:3072
	ds_read_b128 v[146:149], v158
	ds_read_b128 v[150:153], v158 offset:1024
	ds_read_b128 v[154:157], v158 offset:2048
	ds_read_b128 v[158:161], v158 offset:3072
	v_lshl_add_u64 v[194:195], s[36:37], 0, v[210:211]
	s_add_i32 m0, s44, 0xc000
	ds_read_b128 v[162:165], v235
	ds_read_b128 v[166:169], v235 offset:1024
	ds_read_b128 v[170:173], v235 offset:2048
	ds_read_b128 v[174:177], v235 offset:3072
	ds_read_b128 v[178:181], v235 offset:4096
	ds_read_b128 v[182:185], v235 offset:5120
	ds_read_b128 v[186:189], v235 offset:6144
	ds_read_b128 v[190:193], v235 offset:7168
	global_load_lds_dwordx4 v[194:195], off
	v_lshl_add_u64 v[194:195], s[36:37], 0, v[208:209]
	s_add_i32 m0, s44, 0xe000
	s_nop 0
	global_load_lds_dwordx4 v[194:195], off
	s_waitcnt vmcnt(8)
	s_waitcnt lgkmcnt(0)
	s_barrier
	s_setprio 1
	s_waitcnt lgkmcnt(0)
	v_mfma_f32_16x16x32_bf16 v[122:125], v[130:133], v[162:165], 0
	v_mfma_f32_16x16x32_bf16 v[126:129], v[138:141], v[162:165], 0
	v_mfma_f32_16x16x32_bf16 v[110:113], v[130:133], v[170:173], 0
	v_mfma_f32_16x16x32_bf16 v[106:109], v[138:141], v[170:173], 0
	v_mfma_f32_16x16x32_bf16 v[94:97], v[130:133], v[178:181], 0
	v_mfma_f32_16x16x32_bf16 v[90:93], v[138:141], v[178:181], 0
	v_mfma_f32_16x16x32_bf16 v[78:81], v[130:133], v[186:189], 0
	v_mfma_f32_16x16x32_bf16 v[74:77], v[138:141], v[186:189], 0
	v_mfma_f32_16x16x32_bf16 v[122:125], v[134:137], v[166:169], v[122:125]
	v_mfma_f32_16x16x32_bf16 v[126:129], v[142:145], v[166:169], v[126:129]
	v_mfma_f32_16x16x32_bf16 v[110:113], v[134:137], v[174:177], v[110:113]
	v_mfma_f32_16x16x32_bf16 v[106:109], v[142:145], v[174:177], v[106:109]
	v_mfma_f32_16x16x32_bf16 v[94:97], v[134:137], v[182:185], v[94:97]
	v_mfma_f32_16x16x32_bf16 v[90:93], v[142:145], v[182:185], v[90:93]
	v_mfma_f32_16x16x32_bf16 v[78:81], v[134:137], v[190:193], v[78:81]
	v_mfma_f32_16x16x32_bf16 v[74:77], v[142:145], v[190:193], v[74:77]
	s_setprio 0
	s_setprio 1
	v_mfma_f32_16x16x32_bf16 v[118:121], v[146:149], v[162:165], 0
	v_mfma_f32_16x16x32_bf16 v[114:117], v[154:157], v[162:165], 0
	v_mfma_f32_16x16x32_bf16 v[102:105], v[146:149], v[170:173], 0
	v_mfma_f32_16x16x32_bf16 v[98:101], v[154:157], v[170:173], 0
	v_mfma_f32_16x16x32_bf16 v[86:89], v[146:149], v[178:181], 0
	v_mfma_f32_16x16x32_bf16 v[82:85], v[154:157], v[178:181], 0
	v_mfma_f32_16x16x32_bf16 v[70:73], v[146:149], v[186:189], 0
	v_mfma_f32_16x16x32_bf16 v[66:69], v[154:157], v[186:189], 0
	v_mfma_f32_16x16x32_bf16 v[118:121], v[150:153], v[166:169], v[118:121]
	v_mfma_f32_16x16x32_bf16 v[114:117], v[158:161], v[166:169], v[114:117]
	v_mfma_f32_16x16x32_bf16 v[102:105], v[150:153], v[174:177], v[102:105]
	v_mfma_f32_16x16x32_bf16 v[98:101], v[158:161], v[174:177], v[98:101]
	v_mfma_f32_16x16x32_bf16 v[86:89], v[150:153], v[182:185], v[86:89]
	v_mfma_f32_16x16x32_bf16 v[82:85], v[158:161], v[182:185], v[82:85]
	v_mfma_f32_16x16x32_bf16 v[70:73], v[150:153], v[190:193], v[70:73]
	v_mfma_f32_16x16x32_bf16 v[66:69], v[158:161], v[190:193], v[66:69]
	s_setprio 0
	s_barrier
; #define PG8_STAGE(bufoff, gbase, voff) do { _Pragma("unroll") for (int _i = 0; _i < 2; ++_i) \
;         __builtin_amdgcn_global_load_lds((const unsigned*)((const char*)(gbase) + (voff)[_i]), (LAS unsigned*)(lds + (bufoff) + ldsw + _i * 8192), 16, 0, 0); } while (0)
; #define PG8_LDA(dst, b, h) do { _Pragma("unroll") for (int m = 0; m < 4; ++m) _Pragma("unroll") for (int k = 0; k < 2; ++k) dst[m][k] = *(const LAS bf16x8*)(lds + PG8_SA(b, h) + aoff + m * 2048 + k * 1024); } while (0)
; #define PG8_MMA(ai, bj, At, Bt) do { __builtin_amdgcn_s_setprio(1); _Pragma("unroll") for (int m = 0; m < 4; ++m) _Pragma("unroll") for (int n = 0; n < 2; ++n) _Pragma("unroll") for (int k = 0; k < 2; ++k) \
;         acc[ai][bj][m][n] = __builtin_amdgcn_mfma_f32_16x16x32_bf16(Bt[n][k], At[m][k], acc[ai][bj][m][n], 0, 0, 0); __builtin_amdgcn_s_setprio(0); } while (0)
; #define PG8_WAIT_V(n) asm volatile("s_waitcnt vmcnt(" #n ")" ::: "memory")
; #define PG8_WAIT_L(n) asm volatile("s_waitcnt lgkmcnt(" #n ")" ::: "memory")
; #define PG8_BAR __builtin_amdgcn_s_barrier()
; #define PG8_SCHED __builtin_amdgcn_sched_barrier(0)
; template <class Epi>
; __device__ __forceinline__ void gemm_phase(LAS unsigned char* lds, const Gemm g, const StaticOrder& S, const Epi& E, const int tid) {
;     ...
;             PG8_LDA(At, 0, 1); PG8_STAGE(PG8_SB(0, 0), b2, voffB); PG8_STAGE(PG8_SB(0, 1), b2 + hstepB, voffB); PG8_STAGE(PG8_SA(0, 0), a2, voffA);
;             PG8_WAIT_V(8); PG8_WAIT_L(0); PG8_BAR; PG8_MMA(1, 0, At, B0); PG8_MMA(1, 1, At, B1); PG8_BAR; PG8_SCHED;
	s_add_i32 s66, s66, s43
	v_lshl_add_u64 v[194:195], s[64:65], 0, v[0:1]
	s_mov_b32 m0, s66
	ds_read_b128 v[162:165], v235 offset:16384
	ds_read_b128 v[166:169], v235 offset:17408
	ds_read_b128 v[170:173], v235 offset:18432
	ds_read_b128 v[174:177], v235 offset:19456
	ds_read_b128 v[178:181], v235 offset:20480
	ds_read_b128 v[182:185], v235 offset:21504
	ds_read_b128 v[186:189], v235 offset:22528
	ds_read_b128 v[190:193], v235 offset:23552
	global_load_lds_dwordx4 v[194:195], off
	s_add_i32 m0, s66, 0x2000
	v_lshl_add_u64 v[212:213], s[64:65], 0, v[206:207]
	s_add_u32 s64, s64, s14
	s_addc_u32 s65, s65, s15
	s_add_i32 s63, s63, s43
	global_load_lds_dwordx4 v[212:213], off
	v_lshl_add_u64 v[214:215], s[64:65], 0, v[0:1]
	s_mov_b32 m0, s63
	v_lshl_add_u64 v[216:217], s[64:65], 0, v[206:207]
	global_load_lds_dwordx4 v[214:215], off
	s_add_i32 m0, s63, 0x2000
	v_lshl_add_u64 v[218:219], s[38:39], 0, v[202:203]
	global_load_lds_dwordx4 v[216:217], off
	s_mov_b32 m0, s44
	v_lshl_add_u64 v[220:221], s[38:39], 0, v[204:205]
	global_load_lds_dwordx4 v[218:219], off
	s_mov_b32 m0, s45
	s_nop 0
	global_load_lds_dwordx4 v[220:221], off
	s_waitcnt vmcnt(8)
	s_waitcnt lgkmcnt(0)
	s_barrier
	s_setprio 1
	s_waitcnt lgkmcnt(0)
	v_mfma_f32_16x16x32_bf16 v[62:65], v[130:133], v[162:165], 0
	v_mfma_f32_16x16x32_bf16 v[58:61], v[138:141], v[162:165], 0
	v_mfma_f32_16x16x32_bf16 v[46:49], v[130:133], v[170:173], 0
	v_mfma_f32_16x16x32_bf16 v[42:45], v[138:141], v[170:173], 0
	v_mfma_f32_16x16x32_bf16 v[30:33], v[130:133], v[178:181], 0
	v_mfma_f32_16x16x32_bf16 v[26:29], v[138:141], v[178:181], 0
	v_mfma_f32_16x16x32_bf16 v[14:17], v[130:133], v[186:189], 0
	v_mfma_f32_16x16x32_bf16 v[10:13], v[138:141], v[186:189], 0
	v_mfma_f32_16x16x32_bf16 v[62:65], v[134:137], v[166:169], v[62:65]
	v_mfma_f32_16x16x32_bf16 v[58:61], v[142:145], v[166:169], v[58:61]
	v_mfma_f32_16x16x32_bf16 v[46:49], v[134:137], v[174:177], v[46:49]
	v_mfma_f32_16x16x32_bf16 v[42:45], v[142:145], v[174:177], v[42:45]
	v_mfma_f32_16x16x32_bf16 v[30:33], v[134:137], v[182:185], v[30:33]
	v_mfma_f32_16x16x32_bf16 v[26:29], v[142:145], v[182:185], v[26:29]
	v_mfma_f32_16x16x32_bf16 v[14:17], v[134:137], v[190:193], v[14:17]
	v_mfma_f32_16x16x32_bf16 v[10:13], v[142:145], v[190:193], v[10:13]
	s_setprio 0
	s_setprio 1
	v_mfma_f32_16x16x32_bf16 v[54:57], v[146:149], v[162:165], 0
	v_mfma_f32_16x16x32_bf16 v[50:53], v[154:157], v[162:165], 0
	v_mfma_f32_16x16x32_bf16 v[38:41], v[146:149], v[170:173], 0
	v_mfma_f32_16x16x32_bf16 v[34:37], v[154:157], v[170:173], 0
	v_mfma_f32_16x16x32_bf16 v[22:25], v[146:149], v[178:181], 0
	v_mfma_f32_16x16x32_bf16 v[18:21], v[154:157], v[178:181], 0
	v_mfma_f32_16x16x32_bf16 v[6:9], v[146:149], v[186:189], 0
	v_mfma_f32_16x16x32_bf16 v[2:5], v[154:157], v[186:189], 0
	v_mfma_f32_16x16x32_bf16 v[54:57], v[150:153], v[166:169], v[54:57]
	v_mfma_f32_16x16x32_bf16 v[50:53], v[158:161], v[166:169], v[50:53]
	v_mfma_f32_16x16x32_bf16 v[38:41], v[150:153], v[174:177], v[38:41]
	v_mfma_f32_16x16x32_bf16 v[34:37], v[158:161], v[174:177], v[34:37]
	v_mfma_f32_16x16x32_bf16 v[22:25], v[150:153], v[182:185], v[22:25]
	v_mfma_f32_16x16x32_bf16 v[18:21], v[158:161], v[182:185], v[18:21]
	v_mfma_f32_16x16x32_bf16 v[6:9], v[150:153], v[190:193], v[6:9]
	v_mfma_f32_16x16x32_bf16 v[2:5], v[158:161], v[190:193], v[2:5]
	s_setprio 0
	s_barrier
	s_branch .Lkl348_sp2

; #define PG8_STAGE(bufoff, gbase, voff) do { _Pragma("unroll") for (int _i = 0; _i < 2; ++_i) \
;         __builtin_amdgcn_global_load_lds((const unsigned*)((const char*)(gbase) + (voff)[_i]), (LAS unsigned*)(lds + (bufoff) + ldsw + _i * 8192), 16, 0, 0); } while (0)
; #define PG8_LDA(dst, b, h) do { _Pragma("unroll") for (int m = 0; m < 4; ++m) _Pragma("unroll") for (int k = 0; k < 2; ++k) dst[m][k] = *(const LAS bf16x8*)(lds + PG8_SA(b, h) + aoff + m * 2048 + k * 1024); } while (0)
; #define PG8_LDB(dst, b, h) do { _Pragma("unroll") for (int n = 0; n < 2; ++n) _Pragma("unroll") for (int k = 0; k < 2; ++k) dst[n][k] = *(const LAS bf16x8*)(lds + PG8_SB(b, h) + boff + n * 2048 + k * 1024); } while (0)
; #define PG8_MMA(ai, bj, At, Bt) do { __builtin_amdgcn_s_setprio(1); _Pragma("unroll") for (int m = 0; m < 4; ++m) _Pragma("unroll") for (int n = 0; n < 2; ++n) _Pragma("unroll") for (int k = 0; k < 2; ++k) \
;         acc[ai][bj][m][n] = __builtin_amdgcn_mfma_f32_16x16x32_bf16(Bt[n][k], At[m][k], acc[ai][bj][m][n], 0, 0, 0); __builtin_amdgcn_s_setprio(0); } while (0)
; #define PG8_WAIT_V(n) asm volatile("s_waitcnt vmcnt(" #n ")" ::: "memory")
; #define PG8_WAIT_L(n) asm volatile("s_waitcnt lgkmcnt(" #n ")" ::: "memory")
; #define PG8_BAR __builtin_amdgcn_s_barrier()
; #define PG8_SCHED __builtin_amdgcn_sched_barrier(0)
; template <class Epi>
; __device__ __forceinline__ void gemm_phase(LAS unsigned char* lds, const Gemm g, const StaticOrder& S, const Epi& E, const int tid) {
;     ...
;             PG8_LDB(B0, 1, 0); PG8_LDB(B1, 1, 1); PG8_SCHED; PG8_LDA(At, 1, 0); PG8_STAGE(PG8_SA(0, 1), a2 + hstepA, voffA);
;             PG8_WAIT_V(8); PG8_WAIT_L(0); PG8_BAR; PG8_MMA(0, 0, At, B0); PG8_MMA(0, 1, At, B1); PG8_BAR; PG8_SCHED;
.Lkl348_sp2:
	s_add_i32 s63, 0, 0x18000
	s_add_i32 s64, 0, 0x1c000
	v_add_u32_e32 v142, s63, v234
	v_add_u32_e32 v158, s64, v234
	ds_read_b128 v[130:133], v142
	ds_read_b128 v[134:137], v142 offset:1024
	ds_read_b128 v[138:141], v142 offset:2048
	ds_read_b128 v[142:145], v142 offset:3072
	ds_read_b128 v[146:149], v158
	ds_read_b128 v[150:153], v158 offset:1024
	ds_read_b128 v[154:157], v158 offset:2048
	ds_read_b128 v[158:161], v158 offset:3072
	s_add_u32 s38, s38, s12
	s_addc_u32 s39, s39, s13
	s_mov_b32 m0, s46
	v_lshl_add_u64 v[222:223], s[38:39], 0, v[202:203]
	ds_read_b128 v[162:165], v235 offset:32768
	ds_read_b128 v[166:169], v235 offset:33792
	ds_read_b128 v[170:173], v235 offset:34816
	ds_read_b128 v[174:177], v235 offset:35840
	ds_read_b128 v[178:181], v235 offset:36864
	ds_read_b128 v[182:185], v235 offset:37888
	ds_read_b128 v[186:189], v235 offset:38912
	ds_read_b128 v[190:193], v235 offset:39936
	global_load_lds_dwordx4 v[222:223], off
	v_lshl_add_u64 v[222:223], s[38:39], 0, v[204:205]
	s_mov_b32 m0, s47
	s_nop 0
	global_load_lds_dwordx4 v[222:223], off
	s_waitcnt vmcnt(8)
	s_waitcnt lgkmcnt(0)
	s_barrier
	s_setprio 1
	s_waitcnt lgkmcnt(0)
	v_mfma_f32_16x16x32_bf16 v[122:125], v[130:133], v[162:165], v[122:125]
	v_mfma_f32_16x16x32_bf16 v[126:129], v[138:141], v[162:165], v[126:129]
	v_mfma_f32_16x16x32_bf16 v[110:113], v[130:133], v[170:173], v[110:113]
	v_mfma_f32_16x16x32_bf16 v[106:109], v[138:141], v[170:173], v[106:109]
	v_mfma_f32_16x16x32_bf16 v[94:97], v[130:133], v[178:181], v[94:97]
	v_mfma_f32_16x16x32_bf16 v[90:93], v[138:141], v[178:181], v[90:93]
	v_mfma_f32_16x16x32_bf16 v[78:81], v[130:133], v[186:189], v[78:81]
	v_mfma_f32_16x16x32_bf16 v[74:77], v[138:141], v[186:189], v[74:77]
	v_mfma_f32_16x16x32_bf16 v[122:125], v[134:137], v[166:169], v[122:125]
	v_mfma_f32_16x16x32_bf16 v[126:129], v[142:145], v[166:169], v[126:129]
	v_mfma_f32_16x16x32_bf16 v[110:113], v[134:137], v[174:177], v[110:113]
	v_mfma_f32_16x16x32_bf16 v[106:109], v[142:145], v[174:177], v[106:109]
	v_mfma_f32_16x16x32_bf16 v[94:97], v[134:137], v[182:185], v[94:97]
	v_mfma_f32_16x16x32_bf16 v[90:93], v[142:145], v[182:185], v[90:93]
	v_mfma_f32_16x16x32_bf16 v[78:81], v[134:137], v[190:193], v[78:81]
	v_mfma_f32_16x16x32_bf16 v[74:77], v[142:145], v[190:193], v[74:77]
	s_setprio 0
	s_setprio 1
	v_mfma_f32_16x16x32_bf16 v[118:121], v[146:149], v[162:165], v[118:121]
	v_mfma_f32_16x16x32_bf16 v[114:117], v[154:157], v[162:165], v[114:117]
	v_mfma_f32_16x16x32_bf16 v[102:105], v[146:149], v[170:173], v[102:105]
	v_mfma_f32_16x16x32_bf16 v[98:101], v[154:157], v[170:173], v[98:101]
	v_mfma_f32_16x16x32_bf16 v[86:89], v[146:149], v[178:181], v[86:89]
	v_mfma_f32_16x16x32_bf16 v[82:85], v[154:157], v[178:181], v[82:85]
	v_mfma_f32_16x16x32_bf16 v[70:73], v[146:149], v[186:189], v[70:73]
	v_mfma_f32_16x16x32_bf16 v[66:69], v[154:157], v[186:189], v[66:69]
	v_mfma_f32_16x16x32_bf16 v[118:121], v[150:153], v[166:169], v[118:121]
	v_mfma_f32_16x16x32_bf16 v[114:117], v[158:161], v[166:169], v[114:117]
	v_mfma_f32_16x16x32_bf16 v[102:105], v[150:153], v[174:177], v[102:105]
	v_mfma_f32_16x16x32_bf16 v[98:101], v[158:161], v[174:177], v[98:101]
	v_mfma_f32_16x16x32_bf16 v[86:89], v[150:153], v[182:185], v[86:89]
	v_mfma_f32_16x16x32_bf16 v[82:85], v[158:161], v[182:185], v[82:85]
	v_mfma_f32_16x16x32_bf16 v[70:73], v[150:153], v[190:193], v[70:73]
	v_mfma_f32_16x16x32_bf16 v[66:69], v[158:161], v[190:193], v[66:69]
	s_setprio 0
	s_barrier
; #define PG8_STAGE(bufoff, gbase, voff) do { _Pragma("unroll") for (int _i = 0; _i < 2; ++_i) \
;         __builtin_amdgcn_global_load_lds((const unsigned*)((const char*)(gbase) + (voff)[_i]), (LAS unsigned*)(lds + (bufoff) + ldsw + _i * 8192), 16, 0, 0); } while (0)
; #define PG8_LDA(dst, b, h) do { _Pragma("unroll") for (int m = 0; m < 4; ++m) _Pragma("unroll") for (int k = 0; k < 2; ++k) dst[m][k] = *(const LAS bf16x8*)(lds + PG8_SA(b, h) + aoff + m * 2048 + k * 1024); } while (0)
; #define PG8_MMA(ai, bj, At, Bt) do { __builtin_amdgcn_s_setprio(1); _Pragma("unroll") for (int m = 0; m < 4; ++m) _Pragma("unroll") for (int n = 0; n < 2; ++n) _Pragma("unroll") for (int k = 0; k < 2; ++k) \
;         acc[ai][bj][m][n] = __builtin_amdgcn_mfma_f32_16x16x32_bf16(Bt[n][k], At[m][k], acc[ai][bj][m][n], 0, 0, 0); __builtin_amdgcn_s_setprio(0); } while (0)
; #define PG8_WAIT_V(n) asm volatile("s_waitcnt vmcnt(" #n ")" ::: "memory")
; #define PG8_WAIT_L(n) asm volatile("s_waitcnt lgkmcnt(" #n ")" ::: "memory")
; #define PG8_BAR __builtin_amdgcn_s_barrier()
; #define PG8_SCHED __builtin_amdgcn_sched_barrier(0)
; template <class Epi>
; __device__ __forceinline__ void gemm_phase(LAS unsigned char* lds, const Gemm g, const StaticOrder& S, const Epi& E, const int tid) {
;     ...
;             PG8_LDA(At, 1, 1); PG8_STAGE(PG8_SB(1, 0), b3, voffB); PG8_STAGE(PG8_SB(1, 1), b3 + hstepB, voffB); PG8_STAGE(PG8_SA(1, 0), a3, voffA);
;             PG8_WAIT_V(8); PG8_WAIT_L(0); PG8_BAR; PG8_MMA(1, 0, At, B0); PG8_MMA(1, 1, At, B1); PG8_BAR; PG8_SCHED;
;         }
	s_add_i32 s38, s63, s43
	v_lshl_add_u64 v[194:195], v[194:195], 0, s[80:81]
	s_mov_b32 m0, s38
	ds_read_b128 v[162:165], v235 offset:49152
	ds_read_b128 v[166:169], v235 offset:50176
	ds_read_b128 v[170:173], v235 offset:51200
	ds_read_b128 v[174:177], v235 offset:52224
	ds_read_b128 v[178:181], v235 offset:53248
	ds_read_b128 v[182:185], v235 offset:54272
	ds_read_b128 v[186:189], v235 offset:55296
	ds_read_b128 v[190:193], v235 offset:56320
	global_load_lds_dwordx4 v[194:195], off
	v_lshl_add_u64 v[194:195], v[212:213], 0, s[80:81]
	s_add_i32 m0, s38, 0x2000
	s_add_i32 s38, s64, s43
	global_load_lds_dwordx4 v[194:195], off
	v_lshl_add_u64 v[194:195], v[214:215], 0, s[80:81]
	s_mov_b32 m0, s38
	s_nop 0
	global_load_lds_dwordx4 v[194:195], off
	v_lshl_add_u64 v[194:195], v[216:217], 0, s[80:81]
	s_add_i32 m0, s38, 0x2000
	s_nop 0
	global_load_lds_dwordx4 v[194:195], off
	v_lshl_add_u64 v[194:195], v[218:219], 0, s[80:81]
	s_mov_b32 m0, s50
	s_nop 0
	global_load_lds_dwordx4 v[194:195], off
	v_lshl_add_u64 v[194:195], v[220:221], 0, s[80:81]
	s_mov_b32 m0, s51
	s_nop 0
	global_load_lds_dwordx4 v[194:195], off
	s_waitcnt vmcnt(8)
	s_waitcnt lgkmcnt(0)
	s_barrier
	s_setprio 1
	s_waitcnt lgkmcnt(0)
	v_mfma_f32_16x16x32_bf16 v[62:65], v[130:133], v[162:165], v[62:65]
	v_mfma_f32_16x16x32_bf16 v[58:61], v[138:141], v[162:165], v[58:61]
	v_mfma_f32_16x16x32_bf16 v[46:49], v[130:133], v[170:173], v[46:49]
	v_mfma_f32_16x16x32_bf16 v[42:45], v[138:141], v[170:173], v[42:45]
	v_mfma_f32_16x16x32_bf16 v[30:33], v[130:133], v[178:181], v[30:33]
	v_mfma_f32_16x16x32_bf16 v[26:29], v[138:141], v[178:181], v[26:29]
	v_mfma_f32_16x16x32_bf16 v[14:17], v[130:133], v[186:189], v[14:17]
	v_mfma_f32_16x16x32_bf16 v[10:13], v[138:141], v[186:189], v[10:13]
	v_mfma_f32_16x16x32_bf16 v[62:65], v[134:137], v[166:169], v[62:65]
	v_mfma_f32_16x16x32_bf16 v[58:61], v[142:145], v[166:169], v[58:61]
	v_mfma_f32_16x16x32_bf16 v[46:49], v[134:137], v[174:177], v[46:49]
	v_mfma_f32_16x16x32_bf16 v[42:45], v[142:145], v[174:177], v[42:45]
	v_mfma_f32_16x16x32_bf16 v[30:33], v[134:137], v[182:185], v[30:33]
	v_mfma_f32_16x16x32_bf16 v[26:29], v[142:145], v[182:185], v[26:29]
	v_mfma_f32_16x16x32_bf16 v[14:17], v[134:137], v[190:193], v[14:17]
	v_mfma_f32_16x16x32_bf16 v[10:13], v[142:145], v[190:193], v[10:13]
	s_setprio 0
	s_setprio 1
	v_mfma_f32_16x16x32_bf16 v[54:57], v[146:149], v[162:165], v[54:57]
	v_mfma_f32_16x16x32_bf16 v[50:53], v[154:157], v[162:165], v[50:53]
	v_mfma_f32_16x16x32_bf16 v[38:41], v[146:149], v[170:173], v[38:41]
	v_mfma_f32_16x16x32_bf16 v[34:37], v[154:157], v[170:173], v[34:37]
	v_mfma_f32_16x16x32_bf16 v[22:25], v[146:149], v[178:181], v[22:25]
	v_mfma_f32_16x16x32_bf16 v[18:21], v[154:157], v[178:181], v[18:21]
	v_mfma_f32_16x16x32_bf16 v[6:9], v[146:149], v[186:189], v[6:9]
	v_mfma_f32_16x16x32_bf16 v[2:5], v[154:157], v[186:189], v[2:5]
	v_mfma_f32_16x16x32_bf16 v[54:57], v[150:153], v[166:169], v[54:57]
	v_mfma_f32_16x16x32_bf16 v[50:53], v[158:161], v[166:169], v[50:53]
	v_mfma_f32_16x16x32_bf16 v[38:41], v[150:153], v[174:177], v[38:41]
	v_mfma_f32_16x16x32_bf16 v[34:37], v[158:161], v[174:177], v[34:37]
	v_mfma_f32_16x16x32_bf16 v[22:25], v[150:153], v[182:185], v[22:25]
	v_mfma_f32_16x16x32_bf16 v[18:21], v[158:161], v[182:185], v[18:21]
	v_mfma_f32_16x16x32_bf16 v[6:9], v[150:153], v[190:193], v[6:9]
	v_mfma_f32_16x16x32_bf16 v[2:5], v[158:161], v[190:193], v[2:5]
	s_setprio 0
	s_barrier
	s_add_u32 s0, s0, 0x100
	s_addc_u32 s1, s1, 0
	s_add_u32 s36, s36, 0x100
	s_addc_u32 s37, s37, 0
	s_cmp_ge_i32 s62, s53
	s_mov_b32 s38, s62
	s_cbranch_scc0 .LBB0_348

; #define PG8_STAGE(bufoff, gbase, voff) do { _Pragma("unroll") for (int _i = 0; _i < 2; ++_i) \
;         __builtin_amdgcn_global_load_lds((const unsigned*)((const char*)(gbase) + (voff)[_i]), (LAS unsigned*)(lds + (bufoff) + ldsw + _i * 8192), 16, 0, 0); } while (0)
; #define PG8_LDA(dst, b, h) do { _Pragma("unroll") for (int m = 0; m < 4; ++m) _Pragma("unroll") for (int k = 0; k < 2; ++k) dst[m][k] = *(const LAS bf16x8*)(lds + PG8_SA(b, h) + aoff + m * 2048 + k * 1024); } while (0)
; #define PG8_LDB(dst, b, h) do { _Pragma("unroll") for (int n = 0; n < 2; ++n) _Pragma("unroll") for (int k = 0; k < 2; ++k) dst[n][k] = *(const LAS bf16x8*)(lds + PG8_SB(b, h) + boff + n * 2048 + k * 1024); } while (0)
; #define PG8_MMA(ai, bj, At, Bt) do { __builtin_amdgcn_s_setprio(1); _Pragma("unroll") for (int m = 0; m < 4; ++m) _Pragma("unroll") for (int n = 0; n < 2; ++n) _Pragma("unroll") for (int k = 0; k < 2; ++k) \
;         acc[ai][bj][m][n] = __builtin_amdgcn_mfma_f32_16x16x32_bf16(Bt[n][k], At[m][k], acc[ai][bj][m][n], 0, 0, 0); __builtin_amdgcn_s_setprio(0); } while (0)
; template <class Epi>
; __device__ __forceinline__ void gemm_phase(LAS unsigned char* lds, const Gemm g, const StaticOrder& S, const Epi& E, const int tid) {
;     ...
;         const bool has_next = S.next(ui + 1, nxt);
;         const char* nA = has_next ? (const char*)g.A + (size_t)nxt.pm * tstepA + (size_t)((nxt.pn >> g.ashift) * g.astep) * 2 : cA; const char* nB = has_next ? (const char*)g.Bt + (size_t)nxt.pn * tstepB : cB;
;         for (int t = 0; t < nt; t += 2) {
;             const bool last = (t == nt - 2);
;             const char* a1 = cA + (size_t)(t + 1) * kstep;
;             const char* a2 = last ? nA : cA + (size_t)(t + 2) * kstep; const char* b2 = last ? nB : cB + (size_t)(t + 2) * kstep;
;             const char* a3 = a2 + kstep; const char* b3 = b2 + kstep;
;             PG8_LDB(B0, 0, 0); PG8_LDB(B1, 0, 1); PG8_SCHED; PG8_LDA(At, 0, 0); PG8_STAGE(PG8_SA(1, 1), a1 + hstepA, voffA);
;             PG8_WAIT_V(8); PG8_WAIT_L(0); PG8_BAR; PG8_MMA(0, 0, At, B0); PG8_MMA(0, 1, At, B1); PG8_BAR; PG8_SCHED;
;             PG8_LDA(At, 0, 1); PG8_STAGE(PG8_SB(0, 0), b2, voffB); PG8_STAGE(PG8_SB(0, 1), b2 + hstepB, voffB); PG8_STAGE(PG8_SA(0, 0), a2, voffA);
;             PG8_WAIT_V(8); PG8_WAIT_L(0); PG8_BAR; PG8_MMA(1, 0, At, B0); PG8_MMA(1, 1, At, B1); PG8_BAR; PG8_SCHED;
.LBB0_425:
	v_mov_b32_e32 v145, 0
	s_andn2_b64 vcc, exec, s[48:49]
	s_cbranch_vccnz .LBB0_428
	s_add_u32 s0, s66, 0x100
	s_addc_u32 s1, s67, 0
	s_add_u32 s6, s68, 0x80
	s_addc_u32 s7, s69, 0
	s_mov_b32 s8, 0
	s_add_i32 s10, s8, 2
	s_add_u32 s11, s6, 0x80
	s_addc_u32 s9, s7, 0
	s_add_i32 s66, 0, 0x10000
	s_cmp_eq_u32 s43, s8
	s_cselect_b32 s9, s63, s9
	s_cselect_b32 s8, s62, s11
	s_cselect_b32 s13, s65, s1
	s_cselect_b32 s12, s64, s0
	s_add_i32 s11, 0, 0x14000
	v_add_u32_e32 v78, s66, v222
	v_add_u32_e32 v168, s11, v222
	ds_read_b128 v[66:69], v78
	ds_read_b128 v[70:73], v78 offset:1024
	ds_read_b128 v[74:77], v78 offset:2048
	ds_read_b128 v[78:81], v78 offset:3072
	ds_read_b128 v[156:159], v168
	ds_read_b128 v[160:163], v168 offset:1024
	ds_read_b128 v[164:167], v168 offset:2048
	ds_read_b128 v[168:171], v168 offset:3072
	v_lshl_add_u64 v[210:211], s[6:7], 0, v[154:155]
	s_add_i32 m0, s44, 0xc000
	ds_read_b128 v[172:175], v223
	ds_read_b128 v[176:179], v223 offset:1024
	ds_read_b128 v[180:183], v223 offset:2048
	ds_read_b128 v[184:187], v223 offset:3072
	ds_read_b128 v[188:191], v223 offset:4096
	ds_read_b128 v[192:195], v223 offset:5120
	ds_read_b128 v[202:205], v223 offset:6144
	ds_read_b128 v[206:209], v223 offset:7168
	global_load_lds_dwordx4 v[210:211], off
	v_lshl_add_u64 v[210:211], s[6:7], 0, v[152:153]
	s_add_i32 m0, s44, 0xe000
	s_nop 0
	global_load_lds_dwordx4 v[210:211], off
	s_waitcnt vmcnt(8)
	s_waitcnt lgkmcnt(0)
	s_barrier
	s_setprio 1
	s_waitcnt lgkmcnt(0)
	v_mfma_f32_16x16x32_bf16 v[142:145], v[66:69], v[172:175], 0
	v_mfma_f32_16x16x32_bf16 v[138:141], v[74:77], v[172:175], 0
	v_mfma_f32_16x16x32_bf16 v[126:129], v[66:69], v[180:183], 0
	v_mfma_f32_16x16x32_bf16 v[122:125], v[74:77], v[180:183], 0
	v_mfma_f32_16x16x32_bf16 v[110:113], v[66:69], v[188:191], 0
	v_mfma_f32_16x16x32_bf16 v[106:109], v[74:77], v[188:191], 0
	v_mfma_f32_16x16x32_bf16 v[94:97], v[66:69], v[202:205], 0
	v_mfma_f32_16x16x32_bf16 v[90:93], v[74:77], v[202:205], 0
	v_mfma_f32_16x16x32_bf16 v[142:145], v[70:73], v[176:179], v[142:145]
	v_mfma_f32_16x16x32_bf16 v[138:141], v[78:81], v[176:179], v[138:141]
	v_mfma_f32_16x16x32_bf16 v[126:129], v[70:73], v[184:187], v[126:129]
	v_mfma_f32_16x16x32_bf16 v[122:125], v[78:81], v[184:187], v[122:125]
	v_mfma_f32_16x16x32_bf16 v[110:113], v[70:73], v[192:195], v[110:113]
	v_mfma_f32_16x16x32_bf16 v[106:109], v[78:81], v[192:195], v[106:109]
	v_mfma_f32_16x16x32_bf16 v[94:97], v[70:73], v[206:209], v[94:97]
	v_mfma_f32_16x16x32_bf16 v[90:93], v[78:81], v[206:209], v[90:93]
	s_setprio 0
	s_setprio 1
	v_mfma_f32_16x16x32_bf16 v[134:137], v[156:159], v[172:175], 0
	v_mfma_f32_16x16x32_bf16 v[130:133], v[164:167], v[172:175], 0
	v_mfma_f32_16x16x32_bf16 v[118:121], v[156:159], v[180:183], 0
	v_mfma_f32_16x16x32_bf16 v[114:117], v[164:167], v[180:183], 0
	v_mfma_f32_16x16x32_bf16 v[102:105], v[156:159], v[188:191], 0
	v_mfma_f32_16x16x32_bf16 v[98:101], v[164:167], v[188:191], 0
	v_mfma_f32_16x16x32_bf16 v[86:89], v[156:159], v[202:205], 0
	v_mfma_f32_16x16x32_bf16 v[82:85], v[164:167], v[202:205], 0
	v_mfma_f32_16x16x32_bf16 v[134:137], v[160:163], v[176:179], v[134:137]
	v_mfma_f32_16x16x32_bf16 v[130:133], v[168:171], v[176:179], v[130:133]
	v_mfma_f32_16x16x32_bf16 v[118:121], v[160:163], v[184:187], v[118:121]
	v_mfma_f32_16x16x32_bf16 v[114:117], v[168:171], v[184:187], v[114:117]
	v_mfma_f32_16x16x32_bf16 v[102:105], v[160:163], v[192:195], v[102:105]
	v_mfma_f32_16x16x32_bf16 v[98:101], v[168:171], v[192:195], v[98:101]
	v_mfma_f32_16x16x32_bf16 v[86:89], v[160:163], v[206:209], v[86:89]
	v_mfma_f32_16x16x32_bf16 v[82:85], v[168:171], v[206:209], v[82:85]
	s_setprio 0
	s_barrier
	s_add_i32 s66, s66, s85
	v_lshl_add_u64 v[210:211], s[12:13], 0, v[0:1]
	s_mov_b32 m0, s66
	ds_read_b128 v[172:175], v223 offset:16384
	ds_read_b128 v[176:179], v223 offset:17408
	ds_read_b128 v[180:183], v223 offset:18432
	ds_read_b128 v[184:187], v223 offset:19456
	ds_read_b128 v[188:191], v223 offset:20480
	ds_read_b128 v[192:195], v223 offset:21504
	ds_read_b128 v[202:205], v223 offset:22528
	ds_read_b128 v[206:209], v223 offset:23552
	global_load_lds_dwordx4 v[210:211], off
	s_add_i32 m0, s66, 0x2000
	v_lshl_add_u64 v[212:213], s[12:13], 0, v[150:151]
	s_add_u32 s12, s12, s26
	s_addc_u32 s13, s13, s27
	s_add_i32 s11, s11, s85
	global_load_lds_dwordx4 v[212:213], off
	v_lshl_add_u64 v[214:215], s[12:13], 0, v[0:1]
	s_mov_b32 m0, s11
	v_lshl_add_u64 v[216:217], s[12:13], 0, v[150:151]
	global_load_lds_dwordx4 v[214:215], off
	s_add_i32 m0, s11, 0x2000
	v_lshl_add_u64 v[218:219], s[8:9], 0, v[146:147]
	global_load_lds_dwordx4 v[216:217], off
	s_mov_b32 m0, s44
	v_lshl_add_u64 v[220:221], s[8:9], 0, v[148:149]
	global_load_lds_dwordx4 v[218:219], off
	s_mov_b32 m0, s45
	s_nop 0
	global_load_lds_dwordx4 v[220:221], off
	s_waitcnt vmcnt(8)
	s_waitcnt lgkmcnt(0)
	s_barrier
	s_setprio 1
	s_waitcnt lgkmcnt(0)
	v_mfma_f32_16x16x32_bf16 v[62:65], v[66:69], v[172:175], 0
	v_mfma_f32_16x16x32_bf16 v[58:61], v[74:77], v[172:175], 0
	v_mfma_f32_16x16x32_bf16 v[46:49], v[66:69], v[180:183], 0
	v_mfma_f32_16x16x32_bf16 v[42:45], v[74:77], v[180:183], 0
	v_mfma_f32_16x16x32_bf16 v[30:33], v[66:69], v[188:191], 0
	v_mfma_f32_16x16x32_bf16 v[26:29], v[74:77], v[188:191], 0
	v_mfma_f32_16x16x32_bf16 v[14:17], v[66:69], v[202:205], 0
	v_mfma_f32_16x16x32_bf16 v[10:13], v[74:77], v[202:205], 0
	v_mfma_f32_16x16x32_bf16 v[62:65], v[70:73], v[176:179], v[62:65]
	v_mfma_f32_16x16x32_bf16 v[58:61], v[78:81], v[176:179], v[58:61]
	v_mfma_f32_16x16x32_bf16 v[46:49], v[70:73], v[184:187], v[46:49]
	v_mfma_f32_16x16x32_bf16 v[42:45], v[78:81], v[184:187], v[42:45]
	v_mfma_f32_16x16x32_bf16 v[30:33], v[70:73], v[192:195], v[30:33]
	v_mfma_f32_16x16x32_bf16 v[26:29], v[78:81], v[192:195], v[26:29]
	v_mfma_f32_16x16x32_bf16 v[14:17], v[70:73], v[206:209], v[14:17]
	v_mfma_f32_16x16x32_bf16 v[10:13], v[78:81], v[206:209], v[10:13]
	s_setprio 0
	s_setprio 1
	v_mfma_f32_16x16x32_bf16 v[54:57], v[156:159], v[172:175], 0
	v_mfma_f32_16x16x32_bf16 v[50:53], v[164:167], v[172:175], 0
	v_mfma_f32_16x16x32_bf16 v[38:41], v[156:159], v[180:183], 0
	v_mfma_f32_16x16x32_bf16 v[34:37], v[164:167], v[180:183], 0
	v_mfma_f32_16x16x32_bf16 v[22:25], v[156:159], v[188:191], 0
	v_mfma_f32_16x16x32_bf16 v[18:21], v[164:167], v[188:191], 0
	v_mfma_f32_16x16x32_bf16 v[6:9], v[156:159], v[202:205], 0
	v_mfma_f32_16x16x32_bf16 v[2:5], v[164:167], v[202:205], 0
	v_mfma_f32_16x16x32_bf16 v[54:57], v[160:163], v[176:179], v[54:57]
	v_mfma_f32_16x16x32_bf16 v[50:53], v[168:171], v[176:179], v[50:53]
	v_mfma_f32_16x16x32_bf16 v[38:41], v[160:163], v[184:187], v[38:41]
	v_mfma_f32_16x16x32_bf16 v[34:37], v[168:171], v[184:187], v[34:37]
	v_mfma_f32_16x16x32_bf16 v[22:25], v[160:163], v[192:195], v[22:25]
	v_mfma_f32_16x16x32_bf16 v[18:21], v[168:171], v[192:195], v[18:21]
	v_mfma_f32_16x16x32_bf16 v[6:9], v[160:163], v[206:209], v[6:9]
	v_mfma_f32_16x16x32_bf16 v[2:5], v[168:171], v[206:209], v[2:5]
	s_setprio 0
	s_barrier
	s_branch .Lkl427_sp2

; #define PG8_STAGE(bufoff, gbase, voff) do { _Pragma("unroll") for (int _i = 0; _i < 2; ++_i) \
;         __builtin_amdgcn_global_load_lds((const unsigned*)((const char*)(gbase) + (voff)[_i]), (LAS unsigned*)(lds + (bufoff) + ldsw + _i * 8192), 16, 0, 0); } while (0)
; #define PG8_LDA(dst, b, h) do { _Pragma("unroll") for (int m = 0; m < 4; ++m) _Pragma("unroll") for (int k = 0; k < 2; ++k) dst[m][k] = *(const LAS bf16x8*)(lds + PG8_SA(b, h) + aoff + m * 2048 + k * 1024); } while (0)
; #define PG8_LDB(dst, b, h) do { _Pragma("unroll") for (int n = 0; n < 2; ++n) _Pragma("unroll") for (int k = 0; k < 2; ++k) dst[n][k] = *(const LAS bf16x8*)(lds + PG8_SB(b, h) + boff + n * 2048 + k * 1024); } while (0)
; #define PG8_MMA(ai, bj, At, Bt) do { __builtin_amdgcn_s_setprio(1); _Pragma("unroll") for (int m = 0; m < 4; ++m) _Pragma("unroll") for (int n = 0; n < 2; ++n) _Pragma("unroll") for (int k = 0; k < 2; ++k) \
;         acc[ai][bj][m][n] = __builtin_amdgcn_mfma_f32_16x16x32_bf16(Bt[n][k], At[m][k], acc[ai][bj][m][n], 0, 0, 0); __builtin_amdgcn_s_setprio(0); } while (0)
; #define PG8_WAIT_V(n) asm volatile("s_waitcnt vmcnt(" #n ")" ::: "memory")
; #define PG8_WAIT_L(n) asm volatile("s_waitcnt lgkmcnt(" #n ")" ::: "memory")
; #define PG8_BAR __builtin_amdgcn_s_barrier()
; #define PG8_SCHED __builtin_amdgcn_sched_barrier(0)
; template <class Epi>
; __device__ __forceinline__ void gemm_phase(LAS unsigned char* lds, const Gemm g, const StaticOrder& S, const Epi& E, const int tid) {
;     ...
;             PG8_LDB(B0, 1, 0); PG8_LDB(B1, 1, 1); PG8_SCHED; PG8_LDA(At, 1, 0); PG8_STAGE(PG8_SA(0, 1), a2 + hstepA, voffA);
;             PG8_WAIT_V(8); PG8_WAIT_L(0); PG8_BAR; PG8_MMA(0, 0, At, B0); PG8_MMA(0, 1, At, B1); PG8_BAR; PG8_SCHED;
;             PG8_LDA(At, 1, 1); PG8_STAGE(PG8_SB(1, 0), b3, voffB); PG8_STAGE(PG8_SB(1, 1), b3 + hstepB, voffB); PG8_STAGE(PG8_SA(1, 0), a3, voffA);
;             PG8_WAIT_V(8); PG8_WAIT_L(0); PG8_BAR; PG8_MMA(1, 0, At, B0); PG8_MMA(1, 1, At, B1); PG8_BAR; PG8_SCHED;
;         }
.Lkl427_sp2:
	s_add_i32 s11, 0, 0x18000
	s_add_i32 s12, 0, 0x1c000
	v_add_u32_e32 v78, s11, v222
	v_add_u32_e32 v168, s12, v222
	ds_read_b128 v[66:69], v78
	ds_read_b128 v[70:73], v78 offset:1024
	ds_read_b128 v[74:77], v78 offset:2048
	ds_read_b128 v[78:81], v78 offset:3072
	ds_read_b128 v[156:159], v168
	ds_read_b128 v[160:163], v168 offset:1024
	ds_read_b128 v[164:167], v168 offset:2048
	ds_read_b128 v[168:171], v168 offset:3072
	s_add_u32 s8, s8, s24
	s_addc_u32 s9, s9, s25
	s_mov_b32 m0, s52
	v_lshl_add_u64 v[224:225], s[8:9], 0, v[146:147]
	ds_read_b128 v[172:175], v223 offset:32768
	ds_read_b128 v[176:179], v223 offset:33792
	ds_read_b128 v[180:183], v223 offset:34816
	ds_read_b128 v[184:187], v223 offset:35840
	ds_read_b128 v[188:191], v223 offset:36864
	ds_read_b128 v[192:195], v223 offset:37888
	ds_read_b128 v[202:205], v223 offset:38912
	ds_read_b128 v[206:209], v223 offset:39936
	global_load_lds_dwordx4 v[224:225], off
	v_lshl_add_u64 v[224:225], s[8:9], 0, v[148:149]
	s_mov_b32 m0, s53
	s_nop 0
	global_load_lds_dwordx4 v[224:225], off
	s_waitcnt vmcnt(8)
	s_waitcnt lgkmcnt(0)
	s_barrier
	s_setprio 1
	s_waitcnt lgkmcnt(0)
	v_mfma_f32_16x16x32_bf16 v[142:145], v[66:69], v[172:175], v[142:145]
	v_mfma_f32_16x16x32_bf16 v[138:141], v[74:77], v[172:175], v[138:141]
	v_mfma_f32_16x16x32_bf16 v[126:129], v[66:69], v[180:183], v[126:129]
	v_mfma_f32_16x16x32_bf16 v[122:125], v[74:77], v[180:183], v[122:125]
	v_mfma_f32_16x16x32_bf16 v[110:113], v[66:69], v[188:191], v[110:113]
	v_mfma_f32_16x16x32_bf16 v[106:109], v[74:77], v[188:191], v[106:109]
	v_mfma_f32_16x16x32_bf16 v[94:97], v[66:69], v[202:205], v[94:97]
	v_mfma_f32_16x16x32_bf16 v[90:93], v[74:77], v[202:205], v[90:93]
	v_mfma_f32_16x16x32_bf16 v[142:145], v[70:73], v[176:179], v[142:145]
	v_mfma_f32_16x16x32_bf16 v[138:141], v[78:81], v[176:179], v[138:141]
	v_mfma_f32_16x16x32_bf16 v[126:129], v[70:73], v[184:187], v[126:129]
	v_mfma_f32_16x16x32_bf16 v[122:125], v[78:81], v[184:187], v[122:125]
	v_mfma_f32_16x16x32_bf16 v[110:113], v[70:73], v[192:195], v[110:113]
	v_mfma_f32_16x16x32_bf16 v[106:109], v[78:81], v[192:195], v[106:109]
	v_mfma_f32_16x16x32_bf16 v[94:97], v[70:73], v[206:209], v[94:97]
	v_mfma_f32_16x16x32_bf16 v[90:93], v[78:81], v[206:209], v[90:93]
	s_setprio 0
	s_setprio 1
	v_mfma_f32_16x16x32_bf16 v[134:137], v[156:159], v[172:175], v[134:137]
	v_mfma_f32_16x16x32_bf16 v[130:133], v[164:167], v[172:175], v[130:133]
	v_mfma_f32_16x16x32_bf16 v[118:121], v[156:159], v[180:183], v[118:121]
	v_mfma_f32_16x16x32_bf16 v[114:117], v[164:167], v[180:183], v[114:117]
	v_mfma_f32_16x16x32_bf16 v[102:105], v[156:159], v[188:191], v[102:105]
	v_mfma_f32_16x16x32_bf16 v[98:101], v[164:167], v[188:191], v[98:101]
	v_mfma_f32_16x16x32_bf16 v[86:89], v[156:159], v[202:205], v[86:89]
	v_mfma_f32_16x16x32_bf16 v[82:85], v[164:167], v[202:205], v[82:85]
	v_mfma_f32_16x16x32_bf16 v[134:137], v[160:163], v[176:179], v[134:137]
	v_mfma_f32_16x16x32_bf16 v[130:133], v[168:171], v[176:179], v[130:133]
	v_mfma_f32_16x16x32_bf16 v[118:121], v[160:163], v[184:187], v[118:121]
	v_mfma_f32_16x16x32_bf16 v[114:117], v[168:171], v[184:187], v[114:117]
	v_mfma_f32_16x16x32_bf16 v[102:105], v[160:163], v[192:195], v[102:105]
	v_mfma_f32_16x16x32_bf16 v[98:101], v[168:171], v[192:195], v[98:101]
	v_mfma_f32_16x16x32_bf16 v[86:89], v[160:163], v[206:209], v[86:89]
	v_mfma_f32_16x16x32_bf16 v[82:85], v[168:171], v[206:209], v[82:85]
	s_setprio 0
	s_barrier
	s_add_i32 s8, s11, s85
	v_lshl_add_u64 v[210:211], v[210:211], 0, s[80:81]
	s_mov_b32 m0, s8
	ds_read_b128 v[172:175], v223 offset:49152
	ds_read_b128 v[176:179], v223 offset:50176
	ds_read_b128 v[180:183], v223 offset:51200
	ds_read_b128 v[184:187], v223 offset:52224
	ds_read_b128 v[188:191], v223 offset:53248
	ds_read_b128 v[192:195], v223 offset:54272
	ds_read_b128 v[202:205], v223 offset:55296
	ds_read_b128 v[206:209], v223 offset:56320
	global_load_lds_dwordx4 v[210:211], off
	v_lshl_add_u64 v[210:211], v[212:213], 0, s[80:81]
	s_add_i32 m0, s8, 0x2000
	s_add_i32 s8, s12, s85
	global_load_lds_dwordx4 v[210:211], off
	v_lshl_add_u64 v[210:211], v[214:215], 0, s[80:81]
	s_mov_b32 m0, s8
	s_nop 0
	global_load_lds_dwordx4 v[210:211], off
	v_lshl_add_u64 v[210:211], v[216:217], 0, s[80:81]
	s_add_i32 m0, s8, 0x2000
	s_nop 0
	global_load_lds_dwordx4 v[210:211], off
	v_lshl_add_u64 v[210:211], v[218:219], 0, s[80:81]
	s_mov_b32 m0, s36
	s_nop 0
	global_load_lds_dwordx4 v[210:211], off
	v_lshl_add_u64 v[210:211], v[220:221], 0, s[80:81]
	s_mov_b32 m0, s37
	s_nop 0
	global_load_lds_dwordx4 v[210:211], off
	s_waitcnt vmcnt(8)
	s_waitcnt lgkmcnt(0)
	s_barrier
	s_setprio 1
	s_waitcnt lgkmcnt(0)
	v_mfma_f32_16x16x32_bf16 v[62:65], v[66:69], v[172:175], v[62:65]
	v_mfma_f32_16x16x32_bf16 v[58:61], v[74:77], v[172:175], v[58:61]
	v_mfma_f32_16x16x32_bf16 v[46:49], v[66:69], v[180:183], v[46:49]
	v_mfma_f32_16x16x32_bf16 v[42:45], v[74:77], v[180:183], v[42:45]
	v_mfma_f32_16x16x32_bf16 v[30:33], v[66:69], v[188:191], v[30:33]
	v_mfma_f32_16x16x32_bf16 v[26:29], v[74:77], v[188:191], v[26:29]
	v_mfma_f32_16x16x32_bf16 v[14:17], v[66:69], v[202:205], v[14:17]
	v_mfma_f32_16x16x32_bf16 v[10:13], v[74:77], v[202:205], v[10:13]
	v_mfma_f32_16x16x32_bf16 v[62:65], v[70:73], v[176:179], v[62:65]
	v_mfma_f32_16x16x32_bf16 v[58:61], v[78:81], v[176:179], v[58:61]
	v_mfma_f32_16x16x32_bf16 v[46:49], v[70:73], v[184:187], v[46:49]
	v_mfma_f32_16x16x32_bf16 v[42:45], v[78:81], v[184:187], v[42:45]
	v_mfma_f32_16x16x32_bf16 v[30:33], v[70:73], v[192:195], v[30:33]
	v_mfma_f32_16x16x32_bf16 v[26:29], v[78:81], v[192:195], v[26:29]
	v_mfma_f32_16x16x32_bf16 v[14:17], v[70:73], v[206:209], v[14:17]
	v_mfma_f32_16x16x32_bf16 v[10:13], v[78:81], v[206:209], v[10:13]
	s_setprio 0
	s_setprio 1
	v_mfma_f32_16x16x32_bf16 v[54:57], v[156:159], v[172:175], v[54:57]
	v_mfma_f32_16x16x32_bf16 v[50:53], v[164:167], v[172:175], v[50:53]
	v_mfma_f32_16x16x32_bf16 v[38:41], v[156:159], v[180:183], v[38:41]
	v_mfma_f32_16x16x32_bf16 v[34:37], v[164:167], v[180:183], v[34:37]
	v_mfma_f32_16x16x32_bf16 v[22:25], v[156:159], v[188:191], v[22:25]
	v_mfma_f32_16x16x32_bf16 v[18:21], v[164:167], v[188:191], v[18:21]
	v_mfma_f32_16x16x32_bf16 v[6:9], v[156:159], v[202:205], v[6:9]
	v_mfma_f32_16x16x32_bf16 v[2:5], v[164:167], v[202:205], v[2:5]
	v_mfma_f32_16x16x32_bf16 v[54:57], v[160:163], v[176:179], v[54:57]
	v_mfma_f32_16x16x32_bf16 v[50:53], v[168:171], v[176:179], v[50:53]
	v_mfma_f32_16x16x32_bf16 v[38:41], v[160:163], v[184:187], v[38:41]
	v_mfma_f32_16x16x32_bf16 v[34:37], v[168:171], v[184:187], v[34:37]
	v_mfma_f32_16x16x32_bf16 v[22:25], v[160:163], v[192:195], v[22:25]
	v_mfma_f32_16x16x32_bf16 v[18:21], v[168:171], v[192:195], v[18:21]
	v_mfma_f32_16x16x32_bf16 v[6:9], v[160:163], v[206:209], v[6:9]
	v_mfma_f32_16x16x32_bf16 v[2:5], v[168:171], v[206:209], v[2:5]
	s_setprio 0
	s_barrier
	s_add_u32 s0, s0, 0x100
	s_addc_u32 s1, s1, 0
	s_add_u32 s6, s6, 0x100
	s_addc_u32 s7, s7, 0
	s_cmp_ge_i32 s10, s35
	s_mov_b32 s8, s10
	s_cbranch_scc0 .LBB0_427

; #define PG8_STAGE(bufoff, gbase, voff) do { _Pragma("unroll") for (int _i = 0; _i < 2; ++_i) \
;         __builtin_amdgcn_global_load_lds((const unsigned*)((const char*)(gbase) + (voff)[_i]), (LAS unsigned*)(lds + (bufoff) + ldsw + _i * 8192), 16, 0, 0); } while (0)
; #define PG8_LDA(dst, b, h) do { _Pragma("unroll") for (int m = 0; m < 4; ++m) _Pragma("unroll") for (int k = 0; k < 2; ++k) dst[m][k] = *(const LAS bf16x8*)(lds + PG8_SA(b, h) + aoff + m * 2048 + k * 1024); } while (0)
; #define PG8_LDB(dst, b, h) do { _Pragma("unroll") for (int n = 0; n < 2; ++n) _Pragma("unroll") for (int k = 0; k < 2; ++k) dst[n][k] = *(const LAS bf16x8*)(lds + PG8_SB(b, h) + boff + n * 2048 + k * 1024); } while (0)
; #define PG8_MMA(ai, bj, At, Bt) do { __builtin_amdgcn_s_setprio(1); _Pragma("unroll") for (int m = 0; m < 4; ++m) _Pragma("unroll") for (int n = 0; n < 2; ++n) _Pragma("unroll") for (int k = 0; k < 2; ++k) \
;         acc[ai][bj][m][n] = __builtin_amdgcn_mfma_f32_16x16x32_bf16(Bt[n][k], At[m][k], acc[ai][bj][m][n], 0, 0, 0); __builtin_amdgcn_s_setprio(0); } while (0)
; #define PG8_WAIT_V(n) asm volatile("s_waitcnt vmcnt(" #n ")" ::: "memory")
; #define PG8_WAIT_L(n) asm volatile("s_waitcnt lgkmcnt(" #n ")" ::: "memory")
; #define PG8_BAR __builtin_amdgcn_s_barrier()
; #define PG8_SCHED __builtin_amdgcn_sched_barrier(0)
; template <class Epi>
; __device__ __forceinline__ void gemm_phase(LAS unsigned char* lds, const Gemm g, const StaticOrder& S, const Epi& E, const int tid) {
;     ...
;         const bool has_next = S.next(ui + 1, nxt);
;         const char* nA = has_next ? (const char*)g.A + (size_t)nxt.pm * tstepA + (size_t)((nxt.pn >> g.ashift) * g.astep) * 2 : cA; const char* nB = has_next ? (const char*)g.Bt + (size_t)nxt.pn * tstepB : cB;
;         for (int t = 0; t < nt; t += 2) {
;             const bool last = (t == nt - 2);
;             const char* a1 = cA + (size_t)(t + 1) * kstep;
;             const char* a2 = last ? nA : cA + (size_t)(t + 2) * kstep; const char* b2 = last ? nB : cB + (size_t)(t + 2) * kstep;
;             const char* a3 = a2 + kstep; const char* b3 = b2 + kstep;
;             PG8_LDB(B0, 0, 0); PG8_LDB(B1, 0, 1); PG8_SCHED; PG8_LDA(At, 0, 0); PG8_STAGE(PG8_SA(1, 1), a1 + hstepA, voffA);
;             PG8_WAIT_V(8); PG8_WAIT_L(0); PG8_BAR; PG8_MMA(0, 0, At, B0); PG8_MMA(0, 1, At, B1); PG8_BAR; PG8_SCHED;
.LBB0_650:
	v_mov_b32_e32 v113, 0
	s_andn2_b64 vcc, exec, s[24:25]
	s_cbranch_vccnz .LBB0_653
	s_add_u32 s21, s8, 0x100
	s_addc_u32 s42, s9, 0
	s_add_u32 s6, s10, 0x80
	s_addc_u32 s7, s11, 0
	s_mov_b32 s8, 0
	s_add_i32 s10, s8, 2
	s_add_u32 s11, s6, 0x80
	s_addc_u32 s9, s7, 0
	s_add_i32 s43, 0, 0x10000
	s_cmp_eq_u32 s67, s8
	s_cselect_b32 s9, s39, s9
	s_cselect_b32 s8, s38, s11
	v_add_u32_e32 v0, s43, v204
	s_cselect_b32 s45, s41, s42
	s_cselect_b32 s44, s40, s21
	s_add_i32 s11, 0, 0x14000
	ds_read_b128 v[130:133], v0
	ds_read_b128 v[134:137], v0 offset:1024
	ds_read_b128 v[138:141], v0 offset:2048
	ds_read_b128 v[142:145], v0 offset:3072
	v_add_u32_e32 v0, s11, v204
	ds_read_b128 v[146:149], v0
	ds_read_b128 v[150:153], v0 offset:1024
	ds_read_b128 v[154:157], v0 offset:2048
	ds_read_b128 v[158:161], v0 offset:3072
	v_lshl_add_u64 v[178:179], s[6:7], 0, v[190:191]
	s_add_i32 m0, s54, 0xc000
	ds_read_b128 v[162:165], v205
	ds_read_b128 v[166:169], v205 offset:1024
	ds_read_b128 v[170:173], v205 offset:2048
	ds_read_b128 v[174:177], v205 offset:3072
	ds_read_b128 v[192:195], v205 offset:4096
	ds_read_b128 v[206:209], v205 offset:5120
	ds_read_b128 v[210:213], v205 offset:6144
	ds_read_b128 v[214:217], v205 offset:7168
	global_load_lds_dwordx4 v[178:179], off
	v_lshl_add_u64 v[178:179], s[6:7], 0, v[188:189]
	s_add_i32 m0, s54, 0xe000
	s_nop 0
	global_load_lds_dwordx4 v[178:179], off
	s_waitcnt vmcnt(8)
	s_waitcnt lgkmcnt(0)
	s_barrier
	s_setprio 1
	s_waitcnt lgkmcnt(0)
	v_mfma_f32_16x16x32_bf16 v[110:113], v[130:133], v[162:165], 0
	v_mfma_f32_16x16x32_bf16 v[106:109], v[138:141], v[162:165], 0
	v_mfma_f32_16x16x32_bf16 v[94:97], v[130:133], v[170:173], 0
	v_mfma_f32_16x16x32_bf16 v[90:93], v[138:141], v[170:173], 0
	v_mfma_f32_16x16x32_bf16 v[114:117], v[130:133], v[192:195], 0
	v_mfma_f32_16x16x32_bf16 v[62:65], v[138:141], v[192:195], 0
	v_mfma_f32_16x16x32_bf16 v[126:129], v[130:133], v[210:213], 0
	v_mfma_f32_16x16x32_bf16 v[70:73], v[138:141], v[210:213], 0
	v_mfma_f32_16x16x32_bf16 v[110:113], v[134:137], v[166:169], v[110:113]
	v_mfma_f32_16x16x32_bf16 v[106:109], v[142:145], v[166:169], v[106:109]
	v_mfma_f32_16x16x32_bf16 v[94:97], v[134:137], v[174:177], v[94:97]
	v_mfma_f32_16x16x32_bf16 v[90:93], v[142:145], v[174:177], v[90:93]
	v_mfma_f32_16x16x32_bf16 v[114:117], v[134:137], v[206:209], v[114:117]
	v_mfma_f32_16x16x32_bf16 v[62:65], v[142:145], v[206:209], v[62:65]
	v_mfma_f32_16x16x32_bf16 v[126:129], v[134:137], v[214:217], v[126:129]
	v_mfma_f32_16x16x32_bf16 v[70:73], v[142:145], v[214:217], v[70:73]
	s_setprio 0
	s_setprio 1
	v_mfma_f32_16x16x32_bf16 v[102:105], v[146:149], v[162:165], 0
	v_mfma_f32_16x16x32_bf16 v[98:101], v[154:157], v[162:165], 0
	v_mfma_f32_16x16x32_bf16 v[86:89], v[146:149], v[170:173], 0
	v_mfma_f32_16x16x32_bf16 v[82:85], v[154:157], v[170:173], 0
	v_mfma_f32_16x16x32_bf16 v[118:121], v[146:149], v[192:195], 0
	v_mfma_f32_16x16x32_bf16 v[58:61], v[154:157], v[192:195], 0
	v_mfma_f32_16x16x32_bf16 v[122:125], v[146:149], v[210:213], 0
	v_mfma_f32_16x16x32_bf16 v[66:69], v[154:157], v[210:213], 0
	v_mfma_f32_16x16x32_bf16 v[102:105], v[150:153], v[166:169], v[102:105]
	v_mfma_f32_16x16x32_bf16 v[98:101], v[158:161], v[166:169], v[98:101]
	v_mfma_f32_16x16x32_bf16 v[86:89], v[150:153], v[174:177], v[86:89]
	v_mfma_f32_16x16x32_bf16 v[82:85], v[158:161], v[174:177], v[82:85]
	v_mfma_f32_16x16x32_bf16 v[118:121], v[150:153], v[206:209], v[118:121]
	v_mfma_f32_16x16x32_bf16 v[58:61], v[158:161], v[206:209], v[58:61]
	v_mfma_f32_16x16x32_bf16 v[122:125], v[150:153], v[214:217], v[122:125]
	v_mfma_f32_16x16x32_bf16 v[66:69], v[158:161], v[214:217], v[66:69]
	s_setprio 0
	s_barrier
; #define PG8_STAGE(bufoff, gbase, voff) do { _Pragma("unroll") for (int _i = 0; _i < 2; ++_i) \
;         __builtin_amdgcn_global_load_lds((const unsigned*)((const char*)(gbase) + (voff)[_i]), (LAS unsigned*)(lds + (bufoff) + ldsw + _i * 8192), 16, 0, 0); } while (0)
; #define PG8_LDA(dst, b, h) do { _Pragma("unroll") for (int m = 0; m < 4; ++m) _Pragma("unroll") for (int k = 0; k < 2; ++k) dst[m][k] = *(const LAS bf16x8*)(lds + PG8_SA(b, h) + aoff + m * 2048 + k * 1024); } while (0)
; #define PG8_MMA(ai, bj, At, Bt) do { __builtin_amdgcn_s_setprio(1); _Pragma("unroll") for (int m = 0; m < 4; ++m) _Pragma("unroll") for (int n = 0; n < 2; ++n) _Pragma("unroll") for (int k = 0; k < 2; ++k) \
;         acc[ai][bj][m][n] = __builtin_amdgcn_mfma_f32_16x16x32_bf16(Bt[n][k], At[m][k], acc[ai][bj][m][n], 0, 0, 0); __builtin_amdgcn_s_setprio(0); } while (0)
; #define PG8_WAIT_V(n) asm volatile("s_waitcnt vmcnt(" #n ")" ::: "memory")
; #define PG8_WAIT_L(n) asm volatile("s_waitcnt lgkmcnt(" #n ")" ::: "memory")
; #define PG8_BAR __builtin_amdgcn_s_barrier()
; #define PG8_SCHED __builtin_amdgcn_sched_barrier(0)
; template <class Epi>
; __device__ __forceinline__ void gemm_phase(LAS unsigned char* lds, const Gemm g, const StaticOrder& S, const Epi& E, const int tid) {
;     ...
;             PG8_LDA(At, 0, 1); PG8_STAGE(PG8_SB(0, 0), b2, voffB); PG8_STAGE(PG8_SB(0, 1), b2 + hstepB, voffB); PG8_STAGE(PG8_SA(0, 0), a2, voffA);
;             PG8_WAIT_V(8); PG8_WAIT_L(0); PG8_BAR; PG8_MMA(1, 0, At, B0); PG8_MMA(1, 1, At, B1); PG8_BAR; PG8_SCHED;
	s_add_i32 s43, s43, s53
	v_lshl_add_u64 v[178:179], s[44:45], 0, v[182:183]
	s_mov_b32 m0, s43
	ds_read_b128 v[162:165], v205 offset:16384
	ds_read_b128 v[166:169], v205 offset:17408
	ds_read_b128 v[170:173], v205 offset:18432
	ds_read_b128 v[174:177], v205 offset:19456
	ds_read_b128 v[192:195], v205 offset:20480
	ds_read_b128 v[206:209], v205 offset:21504
	ds_read_b128 v[210:213], v205 offset:22528
	ds_read_b128 v[214:217], v205 offset:23552
	global_load_lds_dwordx4 v[178:179], off
	s_add_i32 m0, s43, 0x2000
	v_lshl_add_u64 v[202:203], s[44:45], 0, v[186:187]
	s_add_u32 s44, s44, s12
	s_addc_u32 s45, s45, s13
	s_add_i32 s11, s11, s53
	global_load_lds_dwordx4 v[202:203], off
	v_lshl_add_u64 v[218:219], s[44:45], 0, v[182:183]
	s_mov_b32 m0, s11
	v_lshl_add_u64 v[220:221], s[44:45], 0, v[186:187]
	global_load_lds_dwordx4 v[218:219], off
	s_add_i32 m0, s11, 0x2000
	v_lshl_add_u64 v[222:223], s[8:9], 0, v[180:181]
	global_load_lds_dwordx4 v[220:221], off
	s_mov_b32 m0, s54
	v_lshl_add_u64 v[224:225], s[8:9], 0, v[184:185]
	global_load_lds_dwordx4 v[222:223], off
	s_mov_b32 m0, s55
	s_nop 0
	global_load_lds_dwordx4 v[224:225], off
	s_waitcnt vmcnt(8)
	s_waitcnt lgkmcnt(0)
	s_barrier
	s_setprio 1
	s_waitcnt lgkmcnt(0)
	v_mfma_f32_16x16x32_bf16 v[46:49], v[130:133], v[162:165], 0
	v_mfma_f32_16x16x32_bf16 v[30:33], v[138:141], v[162:165], 0
	v_mfma_f32_16x16x32_bf16 v[38:41], v[130:133], v[170:173], 0
	v_mfma_f32_16x16x32_bf16 v[18:21], v[138:141], v[170:173], 0
	v_mfma_f32_16x16x32_bf16 v[50:53], v[130:133], v[192:195], 0
	v_mfma_f32_16x16x32_bf16 v[2:5], v[138:141], v[192:195], 0
	v_mfma_f32_16x16x32_bf16 v[74:77], v[130:133], v[210:213], 0
	v_mfma_f32_16x16x32_bf16 v[10:13], v[138:141], v[210:213], 0
	v_mfma_f32_16x16x32_bf16 v[46:49], v[134:137], v[166:169], v[46:49]
	v_mfma_f32_16x16x32_bf16 v[30:33], v[142:145], v[166:169], v[30:33]
	v_mfma_f32_16x16x32_bf16 v[38:41], v[134:137], v[174:177], v[38:41]
	v_mfma_f32_16x16x32_bf16 v[18:21], v[142:145], v[174:177], v[18:21]
	v_mfma_f32_16x16x32_bf16 v[50:53], v[134:137], v[206:209], v[50:53]
	v_mfma_f32_16x16x32_bf16 v[2:5], v[142:145], v[206:209], v[2:5]
	v_mfma_f32_16x16x32_bf16 v[74:77], v[134:137], v[214:217], v[74:77]
	v_mfma_f32_16x16x32_bf16 v[10:13], v[142:145], v[214:217], v[10:13]
	s_setprio 0
	s_setprio 1
	v_mfma_f32_16x16x32_bf16 v[42:45], v[146:149], v[162:165], 0
	v_mfma_f32_16x16x32_bf16 v[34:37], v[154:157], v[162:165], 0
	v_mfma_f32_16x16x32_bf16 v[26:29], v[146:149], v[170:173], 0
	v_mfma_f32_16x16x32_bf16 v[22:25], v[154:157], v[170:173], 0
	v_mfma_f32_16x16x32_bf16 v[54:57], v[146:149], v[192:195], 0
	v_mfma_f32_16x16x32_bf16 v[6:9], v[154:157], v[192:195], 0
	v_mfma_f32_16x16x32_bf16 v[78:81], v[146:149], v[210:213], 0
	v_mfma_f32_16x16x32_bf16 v[14:17], v[154:157], v[210:213], 0
	v_mfma_f32_16x16x32_bf16 v[42:45], v[150:153], v[166:169], v[42:45]
	v_mfma_f32_16x16x32_bf16 v[34:37], v[158:161], v[166:169], v[34:37]
	v_mfma_f32_16x16x32_bf16 v[26:29], v[150:153], v[174:177], v[26:29]
	v_mfma_f32_16x16x32_bf16 v[22:25], v[158:161], v[174:177], v[22:25]
	v_mfma_f32_16x16x32_bf16 v[54:57], v[150:153], v[206:209], v[54:57]
	v_mfma_f32_16x16x32_bf16 v[6:9], v[158:161], v[206:209], v[6:9]
	v_mfma_f32_16x16x32_bf16 v[78:81], v[150:153], v[214:217], v[78:81]
	v_mfma_f32_16x16x32_bf16 v[14:17], v[158:161], v[214:217], v[14:17]
	s_setprio 0
	s_barrier
	s_branch .Lkl652_sp2

; #define PG8_STAGE(bufoff, gbase, voff) do { _Pragma("unroll") for (int _i = 0; _i < 2; ++_i) \
;         __builtin_amdgcn_global_load_lds((const unsigned*)((const char*)(gbase) + (voff)[_i]), (LAS unsigned*)(lds + (bufoff) + ldsw + _i * 8192), 16, 0, 0); } while (0)
; #define PG8_LDA(dst, b, h) do { _Pragma("unroll") for (int m = 0; m < 4; ++m) _Pragma("unroll") for (int k = 0; k < 2; ++k) dst[m][k] = *(const LAS bf16x8*)(lds + PG8_SA(b, h) + aoff + m * 2048 + k * 1024); } while (0)
; #define PG8_LDB(dst, b, h) do { _Pragma("unroll") for (int n = 0; n < 2; ++n) _Pragma("unroll") for (int k = 0; k < 2; ++k) dst[n][k] = *(const LAS bf16x8*)(lds + PG8_SB(b, h) + boff + n * 2048 + k * 1024); } while (0)
; #define PG8_MMA(ai, bj, At, Bt) do { __builtin_amdgcn_s_setprio(1); _Pragma("unroll") for (int m = 0; m < 4; ++m) _Pragma("unroll") for (int n = 0; n < 2; ++n) _Pragma("unroll") for (int k = 0; k < 2; ++k) \
;         acc[ai][bj][m][n] = __builtin_amdgcn_mfma_f32_16x16x32_bf16(Bt[n][k], At[m][k], acc[ai][bj][m][n], 0, 0, 0); __builtin_amdgcn_s_setprio(0); } while (0)
; #define PG8_WAIT_V(n) asm volatile("s_waitcnt vmcnt(" #n ")" ::: "memory")
; #define PG8_WAIT_L(n) asm volatile("s_waitcnt lgkmcnt(" #n ")" ::: "memory")
; #define PG8_BAR __builtin_amdgcn_s_barrier()
; #define PG8_SCHED __builtin_amdgcn_sched_barrier(0)
; template <class Epi>
; __device__ __forceinline__ void gemm_phase(LAS unsigned char* lds, const Gemm g, const StaticOrder& S, const Epi& E, const int tid) {
;     ...
;             PG8_LDB(B0, 1, 0); PG8_LDB(B1, 1, 1); PG8_SCHED; PG8_LDA(At, 1, 0); PG8_STAGE(PG8_SA(0, 1), a2 + hstepA, voffA);
;             PG8_WAIT_V(8); PG8_WAIT_L(0); PG8_BAR; PG8_MMA(0, 0, At, B0); PG8_MMA(0, 1, At, B1); PG8_BAR; PG8_SCHED;
.Lkl652_sp2:
	s_add_i32 s11, 0, 0x18000
	v_add_u32_e32 v0, s11, v204
	s_add_i32 s43, 0, 0x1c000
	ds_read_b128 v[130:133], v0
	ds_read_b128 v[134:137], v0 offset:1024
	ds_read_b128 v[138:141], v0 offset:2048
	ds_read_b128 v[142:145], v0 offset:3072
	v_add_u32_e32 v0, s43, v204
	ds_read_b128 v[146:149], v0
	ds_read_b128 v[150:153], v0 offset:1024
	ds_read_b128 v[154:157], v0 offset:2048
	ds_read_b128 v[158:161], v0 offset:3072
	s_add_u32 s8, s8, s0
	s_addc_u32 s9, s9, s1
	s_mov_b32 m0, s56
	v_lshl_add_u64 v[226:227], s[8:9], 0, v[180:181]
	ds_read_b128 v[162:165], v205 offset:32768
	ds_read_b128 v[166:169], v205 offset:33792
	ds_read_b128 v[170:173], v205 offset:34816
	ds_read_b128 v[174:177], v205 offset:35840
	ds_read_b128 v[192:195], v205 offset:36864
	ds_read_b128 v[206:209], v205 offset:37888
	ds_read_b128 v[210:213], v205 offset:38912
	ds_read_b128 v[214:217], v205 offset:39936
	global_load_lds_dwordx4 v[226:227], off
	v_lshl_add_u64 v[226:227], s[8:9], 0, v[184:185]
	s_mov_b32 m0, s57
	s_nop 0
	global_load_lds_dwordx4 v[226:227], off
	s_waitcnt vmcnt(8)
	s_waitcnt lgkmcnt(0)
	s_barrier
	s_setprio 1
	s_waitcnt lgkmcnt(0)
	v_mfma_f32_16x16x32_bf16 v[110:113], v[130:133], v[162:165], v[110:113]
	v_mfma_f32_16x16x32_bf16 v[106:109], v[138:141], v[162:165], v[106:109]
	v_mfma_f32_16x16x32_bf16 v[94:97], v[130:133], v[170:173], v[94:97]
	v_mfma_f32_16x16x32_bf16 v[90:93], v[138:141], v[170:173], v[90:93]
	v_mfma_f32_16x16x32_bf16 v[114:117], v[130:133], v[192:195], v[114:117]
	v_mfma_f32_16x16x32_bf16 v[62:65], v[138:141], v[192:195], v[62:65]
	v_mfma_f32_16x16x32_bf16 v[126:129], v[130:133], v[210:213], v[126:129]
	v_mfma_f32_16x16x32_bf16 v[70:73], v[138:141], v[210:213], v[70:73]
	v_mfma_f32_16x16x32_bf16 v[110:113], v[134:137], v[166:169], v[110:113]
	v_mfma_f32_16x16x32_bf16 v[106:109], v[142:145], v[166:169], v[106:109]
	v_mfma_f32_16x16x32_bf16 v[94:97], v[134:137], v[174:177], v[94:97]
	v_mfma_f32_16x16x32_bf16 v[90:93], v[142:145], v[174:177], v[90:93]
	v_mfma_f32_16x16x32_bf16 v[114:117], v[134:137], v[206:209], v[114:117]
	v_mfma_f32_16x16x32_bf16 v[62:65], v[142:145], v[206:209], v[62:65]
	v_mfma_f32_16x16x32_bf16 v[126:129], v[134:137], v[214:217], v[126:129]
	v_mfma_f32_16x16x32_bf16 v[70:73], v[142:145], v[214:217], v[70:73]
	s_setprio 0
	s_setprio 1
	v_mfma_f32_16x16x32_bf16 v[102:105], v[146:149], v[162:165], v[102:105]
	v_mfma_f32_16x16x32_bf16 v[98:101], v[154:157], v[162:165], v[98:101]
	v_mfma_f32_16x16x32_bf16 v[86:89], v[146:149], v[170:173], v[86:89]
	v_mfma_f32_16x16x32_bf16 v[82:85], v[154:157], v[170:173], v[82:85]
	v_mfma_f32_16x16x32_bf16 v[118:121], v[146:149], v[192:195], v[118:121]
	v_mfma_f32_16x16x32_bf16 v[58:61], v[154:157], v[192:195], v[58:61]
	v_mfma_f32_16x16x32_bf16 v[122:125], v[146:149], v[210:213], v[122:125]
	v_mfma_f32_16x16x32_bf16 v[66:69], v[154:157], v[210:213], v[66:69]
	v_mfma_f32_16x16x32_bf16 v[102:105], v[150:153], v[166:169], v[102:105]
	v_mfma_f32_16x16x32_bf16 v[98:101], v[158:161], v[166:169], v[98:101]
	v_mfma_f32_16x16x32_bf16 v[86:89], v[150:153], v[174:177], v[86:89]
	v_mfma_f32_16x16x32_bf16 v[82:85], v[158:161], v[174:177], v[82:85]
	v_mfma_f32_16x16x32_bf16 v[118:121], v[150:153], v[206:209], v[118:121]
	v_mfma_f32_16x16x32_bf16 v[58:61], v[158:161], v[206:209], v[58:61]
	v_mfma_f32_16x16x32_bf16 v[122:125], v[150:153], v[214:217], v[122:125]
	v_mfma_f32_16x16x32_bf16 v[66:69], v[158:161], v[214:217], v[66:69]
	s_setprio 0
	s_barrier
; #define PG8_STAGE(bufoff, gbase, voff) do { _Pragma("unroll") for (int _i = 0; _i < 2; ++_i) \
;         __builtin_amdgcn_global_load_lds((const unsigned*)((const char*)(gbase) + (voff)[_i]), (LAS unsigned*)(lds + (bufoff) + ldsw + _i * 8192), 16, 0, 0); } while (0)
; #define PG8_LDA(dst, b, h) do { _Pragma("unroll") for (int m = 0; m < 4; ++m) _Pragma("unroll") for (int k = 0; k < 2; ++k) dst[m][k] = *(const LAS bf16x8*)(lds + PG8_SA(b, h) + aoff + m * 2048 + k * 1024); } while (0)
; #define PG8_MMA(ai, bj, At, Bt) do { __builtin_amdgcn_s_setprio(1); _Pragma("unroll") for (int m = 0; m < 4; ++m) _Pragma("unroll") for (int n = 0; n < 2; ++n) _Pragma("unroll") for (int k = 0; k < 2; ++k) \
;         acc[ai][bj][m][n] = __builtin_amdgcn_mfma_f32_16x16x32_bf16(Bt[n][k], At[m][k], acc[ai][bj][m][n], 0, 0, 0); __builtin_amdgcn_s_setprio(0); } while (0)
; #define PG8_WAIT_V(n) asm volatile("s_waitcnt vmcnt(" #n ")" ::: "memory")
; #define PG8_WAIT_L(n) asm volatile("s_waitcnt lgkmcnt(" #n ")" ::: "memory")
; #define PG8_BAR __builtin_amdgcn_s_barrier()
; #define PG8_SCHED __builtin_amdgcn_sched_barrier(0)
; template <class Epi>
; __device__ __forceinline__ void gemm_phase(LAS unsigned char* lds, const Gemm g, const StaticOrder& S, const Epi& E, const int tid) {
;     ...
;             PG8_LDA(At, 1, 1); PG8_STAGE(PG8_SB(1, 0), b3, voffB); PG8_STAGE(PG8_SB(1, 1), b3 + hstepB, voffB); PG8_STAGE(PG8_SA(1, 0), a3, voffA);
;             PG8_WAIT_V(8); PG8_WAIT_L(0); PG8_BAR; PG8_MMA(1, 0, At, B0); PG8_MMA(1, 1, At, B1); PG8_BAR; PG8_SCHED;
;         }
	s_add_i32 s8, s11, s53
	v_lshl_add_u64 v[178:179], v[178:179], 0, s[80:81]
	s_mov_b32 m0, s8
	ds_read_b128 v[162:165], v205 offset:49152
	ds_read_b128 v[166:169], v205 offset:50176
	ds_read_b128 v[170:173], v205 offset:51200
	ds_read_b128 v[174:177], v205 offset:52224
	ds_read_b128 v[192:195], v205 offset:53248
	ds_read_b128 v[206:209], v205 offset:54272
	ds_read_b128 v[210:213], v205 offset:55296
	ds_read_b128 v[214:217], v205 offset:56320
	global_load_lds_dwordx4 v[178:179], off
	v_lshl_add_u64 v[178:179], v[202:203], 0, s[80:81]
	s_add_i32 m0, s8, 0x2000
	s_add_i32 s8, s43, s53
	global_load_lds_dwordx4 v[178:179], off
	v_lshl_add_u64 v[178:179], v[218:219], 0, s[80:81]
	s_mov_b32 m0, s8
	s_nop 0
	global_load_lds_dwordx4 v[178:179], off
	v_lshl_add_u64 v[178:179], v[220:221], 0, s[80:81]
	s_add_i32 m0, s8, 0x2000
	s_nop 0
	global_load_lds_dwordx4 v[178:179], off
	v_lshl_add_u64 v[178:179], v[222:223], 0, s[80:81]
	s_mov_b32 m0, s62
	s_nop 0
	global_load_lds_dwordx4 v[178:179], off
	v_lshl_add_u64 v[178:179], v[224:225], 0, s[80:81]
	s_mov_b32 m0, s63
	s_nop 0
	global_load_lds_dwordx4 v[178:179], off
	s_waitcnt vmcnt(8)
	s_waitcnt lgkmcnt(0)
	s_barrier
	s_setprio 1
	s_waitcnt lgkmcnt(0)
	v_mfma_f32_16x16x32_bf16 v[46:49], v[130:133], v[162:165], v[46:49]
	v_mfma_f32_16x16x32_bf16 v[30:33], v[138:141], v[162:165], v[30:33]
	v_mfma_f32_16x16x32_bf16 v[38:41], v[130:133], v[170:173], v[38:41]
	v_mfma_f32_16x16x32_bf16 v[18:21], v[138:141], v[170:173], v[18:21]
	v_mfma_f32_16x16x32_bf16 v[50:53], v[130:133], v[192:195], v[50:53]
	v_mfma_f32_16x16x32_bf16 v[2:5], v[138:141], v[192:195], v[2:5]
	v_mfma_f32_16x16x32_bf16 v[74:77], v[130:133], v[210:213], v[74:77]
	v_mfma_f32_16x16x32_bf16 v[10:13], v[138:141], v[210:213], v[10:13]
	v_mfma_f32_16x16x32_bf16 v[46:49], v[134:137], v[166:169], v[46:49]
	v_mfma_f32_16x16x32_bf16 v[30:33], v[142:145], v[166:169], v[30:33]
	v_mfma_f32_16x16x32_bf16 v[38:41], v[134:137], v[174:177], v[38:41]
	v_mfma_f32_16x16x32_bf16 v[18:21], v[142:145], v[174:177], v[18:21]
	v_mfma_f32_16x16x32_bf16 v[50:53], v[134:137], v[206:209], v[50:53]
	v_mfma_f32_16x16x32_bf16 v[2:5], v[142:145], v[206:209], v[2:5]
	v_mfma_f32_16x16x32_bf16 v[74:77], v[134:137], v[214:217], v[74:77]
	v_mfma_f32_16x16x32_bf16 v[10:13], v[142:145], v[214:217], v[10:13]
	s_setprio 0
	s_setprio 1
	v_mfma_f32_16x16x32_bf16 v[42:45], v[146:149], v[162:165], v[42:45]
	v_mfma_f32_16x16x32_bf16 v[34:37], v[154:157], v[162:165], v[34:37]
	v_mfma_f32_16x16x32_bf16 v[26:29], v[146:149], v[170:173], v[26:29]
	v_mfma_f32_16x16x32_bf16 v[22:25], v[154:157], v[170:173], v[22:25]
	v_mfma_f32_16x16x32_bf16 v[54:57], v[146:149], v[192:195], v[54:57]
	v_mfma_f32_16x16x32_bf16 v[6:9], v[154:157], v[192:195], v[6:9]
	v_mfma_f32_16x16x32_bf16 v[78:81], v[146:149], v[210:213], v[78:81]
	v_mfma_f32_16x16x32_bf16 v[14:17], v[154:157], v[210:213], v[14:17]
	v_mfma_f32_16x16x32_bf16 v[42:45], v[150:153], v[166:169], v[42:45]
	v_mfma_f32_16x16x32_bf16 v[34:37], v[158:161], v[166:169], v[34:37]
	v_mfma_f32_16x16x32_bf16 v[26:29], v[150:153], v[174:177], v[26:29]
	v_mfma_f32_16x16x32_bf16 v[22:25], v[158:161], v[174:177], v[22:25]
	v_mfma_f32_16x16x32_bf16 v[54:57], v[150:153], v[206:209], v[54:57]
	v_mfma_f32_16x16x32_bf16 v[6:9], v[158:161], v[206:209], v[6:9]
	v_mfma_f32_16x16x32_bf16 v[78:81], v[150:153], v[214:217], v[78:81]
	v_mfma_f32_16x16x32_bf16 v[14:17], v[158:161], v[214:217], v[14:17]
	s_setprio 0
	s_barrier
	s_add_u32 s21, s21, 0x100
	s_addc_u32 s42, s42, 0
	s_add_u32 s6, s6, 0x100
	s_addc_u32 s7, s7, 0
	s_cmp_ge_i32 s10, s64
	s_mov_b32 s8, s10
	s_cbranch_scc0 .LBB0_652
